# attention: each wave visits only the 48 key columns its 16 queries can see (3 of 4 column tiles per key row), contiguous-column key tiles, V^T slots interleave the two key rows
# speedup vs baseline: 1.2637x; 1.0051x over previous
; __device__ __forceinline__ void attn_phase(const Params& P, char* smem_raw) {
;   u16* sm_k = reinterpret_cast<u16*>(smem_raw);
;   u16* sm_vt = sm_k + 128 * LDSS;
;   u16* sm_p = sm_vt + 64 * 136;
;   float* sm_rpb = reinterpret_cast<float*>(sm_p + 4 * 16 * 136);
;   const int tid = VTID, lane = tid & 63, wid = tid >> 6;
;   const u16* QKV = P.zq;
;   const u16* VTX = P.zf;
;   const u16* VTC = reinterpret_cast<const u16*>(P.summ);
;   uint4 kreg[4], vreg[4];
;   bf16x8 qn[2];
;     ...
;   int dco[4][4];
; #pragma unroll
;   for (int reg = 0; reg < 4; ++reg) {
;     const int c = wid * 16 + (lane >> 4) * 4 + reg;
;     const int cs = min(max(c - 8, 0), 48);
; #pragma unroll
;     for (int q4 = 0; q4 < 4; ++q4) {
;       const int kc = q4 * 16 + (lane & 15);
;       dco[reg][q4] = (kc >= cs && kc < cs + 16) ? (kc - c + 15) : 465;
;     }
;   }
.LBB0_1489:
	s_cmp_gt_i32 s34, 12
	s_cselect_b64 s[0:1], -1, 0
	s_cmp_lt_i32 s35, 13
	s_cselect_b64 s[4:5], -1, 0
	s_or_b64 s[0:1], s[0:1], s[4:5]
	s_and_b64 vcc, exec, s[0:1]
	s_cbranch_vccnz .LBB0_1555
	s_waitcnt vmcnt(5)
	v_lshl_add_u32 v109, s2, 1, v153
	s_movk_i32 s0, 0x2000
	v_mov_b32_e32 v0, v153
	v_cmp_gt_i32_e32 vcc, s0, v109
	s_barrier
	s_and_saveexec_b64 s[42:43], vcc
	s_cbranch_execz .LBB0_1501
	v_readlane_b32 s0, v252, 0
	v_readlane_b32 s1, v252, 1
	v_readfirstlane_b32 s3, v153
	s_nop 3
	s_sub_u32 s0, s0, 0x170
	s_subb_u32 s1, s1, 0
	s_load_dwordx2 s[12:13], s[0:1], 0xb8
	s_load_dwordx2 s[8:9], s[0:1], 0x130
	s_load_dwordx4 s[4:7], s[0:1], 0x148
	s_load_dwordx2 s[10:11], s[0:1], 0x158
	s_lshl_b32 s100, s2, 1
	s_add_u32 s3, s100, s3
	s_and_b32 s101, s3, 15
	s_lshl_b32 s3, s3, 8
	s_waitcnt lgkmcnt(0)
	s_lshl_b32 s100, s101, 7
	s_add_u32 s4, s4, s100
	s_addc_u32 s5, s5, 0
	s_add_u32 s10, s10, s100
	s_addc_u32 s11, s11, 0
	s_lshl_b32 s100, s101, 20
	s_add_u32 s6, s6, s100
	s_addc_u32 s7, s7, 0
	s_lshl_b32 s100, s101, 15
	s_add_u32 s8, s8, s100
	s_addc_u32 s9, s9, 0
	s_mul_i32 s100, s101, 0x744
	s_add_u32 s12, s12, s100
	s_addc_u32 s13, s13, 0
	v_and_b32_e32 v112, 0xff, v152
	v_and_b32_e32 v113, 63, v152
	v_bfe_u32 v114, v152, 6, 2
	v_lshrrev_b32_e32 v115, 4, v113
	v_and_b32_e32 v116, 15, v113
	v_mul_u32_u24_e32 v117, 0x12000, v153
	v_add_u32_e32 v117, 16, v117
	v_and_b32_e32 v118, 7, v116
	v_lshrrev_b32_e32 v119, 1, v114
	v_lshlrev_b32_e32 v119, 4, v119
	v_xor_b32_e32 v121, v115, v118
	v_lshl_add_u32 v122, v116, 7, v117
	v_lshl_add_u32 v149, v121, 4, v122
	v_xor_b32_e32 v121, 4, v121
	v_lshl_add_u32 v224, v121, 4, v122
	v_lshl_add_u32 v144, v119, 7, v149
	v_lshl_add_u32 v145, v119, 7, v224
	v_lshl_add_u32 v124, v116, 8, v117
	v_add_u32_e32 v124, 0x4000, v124
	v_lshrrev_b32_e32 v123, 2, v119
	v_add_u32_e32 v125, 0, v115
	v_xor_b32_e32 v125, v125, v116
	v_lshl_add_u32 v225, v125, 4, v124
	v_add_u32_e32 v125, 4, v115
	v_xor_b32_e32 v125, v125, v116
	v_lshl_add_u32 v226, v125, 4, v124
	v_add_u32_e32 v125, 8, v115
	v_xor_b32_e32 v125, v125, v116
	v_lshl_add_u32 v227, v125, 4, v124
	v_add_u32_e32 v125, 12, v115
	v_xor_b32_e32 v125, v125, v116
	v_lshl_add_u32 v228, v125, 4, v124
	v_add3_u32 v125, v123, 0, v115
	v_xor_b32_e32 v125, v125, v116
	v_lshl_add_u32 v146, v125, 4, v124
	v_add3_u32 v125, v123, 4, v115
	v_xor_b32_e32 v125, v125, v116
	v_lshl_add_u32 v147, v125, 4, v124
	v_add3_u32 v125, v123, 8, v115
	v_xor_b32_e32 v125, v125, v116
	v_lshl_add_u32 v148, v125, 4, v124
	v_lshrrev_b32_e32 v126, 3, v112
	v_and_b32_e32 v127, 7, v112
	v_and_b32_e32 v128, 7, v126
	v_xor_b32_e32 v128, v127, v128
	v_lshl_add_u32 v125, v126, 7, v117
	v_lshl_add_u32 v150, v128, 4, v125
	v_lshrrev_b32_e32 v129, 4, v112
	v_and_b32_e32 v130, 15, v112
	v_and_b32_e32 v125, 7, v130
	v_lshlrev_b32_e32 v125, 1, v125
	v_xor_b32_e32 v125, v125, v129
	v_lshl_add_u32 v128, v129, 8, v117
	v_lshl_add_u32 v151, v125, 4, v128
	v_xor_b32_e32 v125, 1, v125
	v_lshl_add_u32 v229, v125, 4, v128
	v_lshrrev_b32_e32 v125, 3, v130
	v_lshl_add_u32 v151, v125, 3, v151
	v_lshl_add_u32 v229, v125, 3, v229
	v_add_u32_e32 v151, 0x4000, v151
	v_add_u32_e32 v229, 0x4000, v229
	v_mul_u32_u24_e32 v125, 0x1800, v126
	v_lshl_add_u32 v154, v127, 4, v125
	v_add_u32_e32 v155, 0x30000, v154
	v_add_u32_e32 v156, 0x60000, v154
	v_add_u32_e32 v157, 0x90000, v154
	v_lshlrev_b32_e32 v125, 14, v129
	v_lshl_add_u32 v158, v130, 4, v125
	v_add_u32_e32 v159, 0x40000, v158
	v_add_u32_e32 v160, 0x80000, v158
	v_add_u32_e32 v161, 0xc0000, v158
	v_lshlrev_b32_e32 v125, 9, v129
	v_lshl_add_u32 v162, v130, 4, v125
	v_add_u32_e32 v163, 0x2000, v162
	v_add_u32_e32 v164, 0x4000, v162
	v_add_u32_e32 v165, 0x6000, v162
	v_lshl_add_u32 v131, v114, 4, v116
	v_mul_u32_u24_e32 v125, 0x1800, v131
	v_lshl_add_u32 v166, v115, 4, v125
	v_lshlrev_b32_e32 v125, 11, v131
	v_lshl_add_u32 v167, v115, 3, v125
	v_sub_u32_e64 v132, v131, 8 clamp
	v_min_u32_e32 v132, 48, v132
	v_mov_b32_e32 v210, 0x7c
	v_lshl_add_u32 v133, v115, 2, v119
	v_add_u32_e32 v134, 0, v133
	v_sub_u32_e32 v135, v134, v132
	v_cmp_gt_u32_e32 vcc, 16, v135
	v_sub_u32_e32 v136, v134, v131
	v_lshlrev_b32_e32 v136, 2, v136
	v_add_u32_e32 v136, 60, v136
	v_cndmask_b32_e32 v168, v210, v136, vcc
	v_add_u32_e32 v134, 1, v133
	v_sub_u32_e32 v135, v134, v132
	v_cmp_gt_u32_e32 vcc, 16, v135
	v_sub_u32_e32 v136, v134, v131
	v_lshlrev_b32_e32 v136, 2, v136
	v_add_u32_e32 v136, 60, v136
	v_cndmask_b32_e32 v169, v210, v136, vcc
	v_add_u32_e32 v134, 2, v133
	v_sub_u32_e32 v135, v134, v132
	v_cmp_gt_u32_e32 vcc, 16, v135
	v_sub_u32_e32 v136, v134, v131
	v_lshlrev_b32_e32 v136, 2, v136
	v_add_u32_e32 v136, 60, v136
	v_cndmask_b32_e32 v170, v210, v136, vcc
	v_add_u32_e32 v134, 3, v133
	v_sub_u32_e32 v135, v134, v132
	v_cmp_gt_u32_e32 vcc, 16, v135
	v_sub_u32_e32 v136, v134, v131
	v_lshlrev_b32_e32 v136, 2, v136
	v_add_u32_e32 v136, 60, v136
	v_cndmask_b32_e32 v171, v210, v136, vcc
	v_add_u32_e32 v134, 16, v133
	v_sub_u32_e32 v135, v134, v132
	v_cmp_gt_u32_e32 vcc, 16, v135
	v_sub_u32_e32 v136, v134, v131
	v_lshlrev_b32_e32 v136, 2, v136
	v_add_u32_e32 v136, 60, v136
	v_cndmask_b32_e32 v172, v210, v136, vcc
	v_add_u32_e32 v134, 17, v133
	v_sub_u32_e32 v135, v134, v132
	v_cmp_gt_u32_e32 vcc, 16, v135
	v_sub_u32_e32 v136, v134, v131
	v_lshlrev_b32_e32 v136, 2, v136
	v_add_u32_e32 v136, 60, v136
	v_cndmask_b32_e32 v173, v210, v136, vcc
	v_add_u32_e32 v134, 18, v133
	v_sub_u32_e32 v135, v134, v132
	v_cmp_gt_u32_e32 vcc, 16, v135
	v_sub_u32_e32 v136, v134, v131
	v_lshlrev_b32_e32 v136, 2, v136
	v_add_u32_e32 v136, 60, v136
	v_cndmask_b32_e32 v174, v210, v136, vcc
	v_add_u32_e32 v134, 19, v133
; __device__ __forceinline__ void attn_phase(const Params& P, char* smem_raw) {
;     ...
;   int dco[4][4];
; #pragma unroll
;   for (int reg = 0; reg < 4; ++reg) {
;     const int c = wid * 16 + (lane >> 4) * 4 + reg;
;     const int cs = min(max(c - 8, 0), 48);
; #pragma unroll
;     for (int q4 = 0; q4 < 4; ++q4) {
;       const int kc = q4 * 16 + (lane & 15);
;       dco[reg][q4] = (kc >= cs && kc < cs + 16) ? (kc - c + 15) : 465;
;     }
;   }
;   int t = VBID;
;   __syncthreads();
;   if (t < 8192) {
;     const int h0 = t & 15;
;     for (int idx = tid; idx < 930; idx += VTHR) sm_rpb[idx] = (idx < 465) ? P.rpb[h0 * 465 + idx] * 1.4426950408889634f : -1e30f;
;     ATT_ISSUE(t, 0)
;     ATT_QLOAD(t)
;   }
;   for (; t < 8192; t += VGRID) {
;     const int h = t & 15, r = (t >> 4) & 127, b = t >> 11;
;     const int rs = min(max(r - 4, 0), 120);
;     bf16x8 qf[2];
;     qf[0] = qn[0]; qf[1] = qn[1];
;     f32x4 o[4];
; #pragma unroll
;     for (int td = 0; td < 4; ++td) o[td] = f32x4{0.f, 0.f, 0.f, 0.f};
;     float mrow[4], lrow[4];
; #pragma unroll
;     for (int reg = 0; reg < 4; ++reg) { mrow[reg] = -1e30f; lrow[reg] = 0.f; }
	v_sub_u32_e32 v135, v134, v132
	v_cmp_gt_u32_e32 vcc, 16, v135
	v_sub_u32_e32 v136, v134, v131
	v_lshlrev_b32_e32 v136, 2, v136
	v_add_u32_e32 v136, 60, v136
	v_cndmask_b32_e32 v175, v210, v136, vcc
	v_add_u32_e32 v134, 32, v133
	v_sub_u32_e32 v135, v134, v132
	v_cmp_gt_u32_e32 vcc, 16, v135
	v_sub_u32_e32 v136, v134, v131
	v_lshlrev_b32_e32 v136, 2, v136
	v_add_u32_e32 v136, 60, v136
	v_cndmask_b32_e32 v176, v210, v136, vcc
	v_add_u32_e32 v134, 33, v133
	v_sub_u32_e32 v135, v134, v132
	v_cmp_gt_u32_e32 vcc, 16, v135
	v_sub_u32_e32 v136, v134, v131
	v_lshlrev_b32_e32 v136, 2, v136
	v_add_u32_e32 v136, 60, v136
	v_cndmask_b32_e32 v177, v210, v136, vcc
	v_add_u32_e32 v134, 34, v133
	v_sub_u32_e32 v135, v134, v132
	v_cmp_gt_u32_e32 vcc, 16, v135
	v_sub_u32_e32 v136, v134, v131
	v_lshlrev_b32_e32 v136, 2, v136
	v_add_u32_e32 v136, 60, v136
	v_cndmask_b32_e32 v178, v210, v136, vcc
	v_add_u32_e32 v134, 35, v133
	v_sub_u32_e32 v135, v134, v132
	v_cmp_gt_u32_e32 vcc, 16, v135
	v_sub_u32_e32 v136, v134, v131
	v_lshlrev_b32_e32 v136, 2, v136
	v_add_u32_e32 v136, 60, v136
	v_cndmask_b32_e32 v179, v210, v136, vcc
	v_mov_b32_e32 v143, 0xf149f2ca
	v_mov_b32_e32 v137, v112
	v_lshrrev_b32_e32 v138, 5, v137
	v_and_b32_e32 v139, 31, v137
	v_mul_u32_u24_e32 v140, 31, v138
	v_add_u32_e32 v140, v140, v139
	v_min_u32_e32 v140, 0x1d0, v140
	v_lshlrev_b32_e32 v140, 2, v140
	global_load_dword v141, v140, s[12:13]
	v_lshl_add_u32 v142, v137, 2, v117
	v_add_u32_e32 v142, 0x10000, v142
	v_cmp_eq_u32_e32 vcc, 31, v139
	s_waitcnt vmcnt(0)
	v_mul_f32_e32 v141, 0x3fb8aa3b, v141
	v_cndmask_b32_e32 v141, v141, v143, vcc
	ds_write_b32 v142, v141
	v_add_u32_e32 v137, 0x100, v112
	v_lshrrev_b32_e32 v138, 5, v137
	v_and_b32_e32 v139, 31, v137
	v_mul_u32_u24_e32 v140, 31, v138
	v_add_u32_e32 v140, v140, v139
	v_min_u32_e32 v140, 0x1d0, v140
	v_lshlrev_b32_e32 v140, 2, v140
	global_load_dword v141, v140, s[12:13]
	v_lshl_add_u32 v142, v137, 2, v117
	v_add_u32_e32 v142, 0x10000, v142
	v_cmp_eq_u32_e32 vcc, 31, v139
	s_waitcnt vmcnt(0)
	v_mul_f32_e32 v141, 0x3fb8aa3b, v141
	v_cndmask_b32_e32 v141, v141, v143, vcc
	ds_write_b32 v142, v141
	s_and_b32 s0, s3, 0xff
	s_lshr_b32 s1, s0, 2
	s_and_b32 s0, s0, 3
	s_lshl_b32 s0, s0, 5
	s_lshr_b32 vcc_lo, s3, 12
	s_add_u32 s0, s0, vcc_lo
	s_sub_i32 vcc_lo, s0, 4
	s_max_i32 vcc_lo, vcc_lo, 0
	s_min_i32 vcc_lo, vcc_lo, 0x78
	s_lshl_b32 vcc_hi, s1, 13
	s_lshl_b32 m0, vcc_lo, 6
	s_add_u32 m0, m0, vcc_hi
	s_mul_i32 m0, m0, 0x1800
	s_add_u32 s12, s4, m0
	s_addc_u32 s13, s5, 0
	s_lshl_b32 m0, s1, 24
	s_lshl_b32 s100, vcc_lo, 7
	s_add_u32 m0, m0, s100
	s_add_u32 s14, s6, m0
	s_addc_u32 s15, s7, 0
	s_lshl_b32 m0, s0, 6
	s_add_u32 m0, m0, vcc_hi
	s_mul_i32 m0, m0, 0x1800
	s_add_u32 s100, s4, m0
	s_addc_u32 s101, s5, 0
	global_load_dwordx4 v[64:67], v166, s[100:101]
	global_load_dwordx4 v[68:71], v166, s[100:101] offset:64
	s_and_b32 s0, s3, 0xff
	s_lshr_b32 s1, s0, 2
	s_and_b32 s0, s0, 3
	s_lshl_b32 s0, s0, 5
	s_lshr_b32 vcc_lo, s3, 12
	s_add_u32 s0, s0, vcc_lo
	s_sub_i32 vcc_lo, s0, 4
	s_max_i32 vcc_lo, vcc_lo, 0
	s_min_i32 vcc_lo, vcc_lo, 0x78
	s_lshl_b32 vcc_hi, s1, 13
	s_sub_i32 vcc_lo, vcc_lo, s0
	s_add_i32 vcc_lo, vcc_lo, 4
	s_lshl_b32 vcc_lo, vcc_lo, 7
	s_bfe_u32 m0, s3, 0x10008
	s_mul_i32 m0, m0, 0x12000
	s_add_i32 vcc_lo, vcc_lo, m0
	s_add_i32 vcc_lo, vcc_lo, 0x10010
	v_add_u32_e32 v184, vcc_lo, v168
	v_add_u32_e32 v185, vcc_lo, v169
	v_add_u32_e32 v186, vcc_lo, v170
	v_add_u32_e32 v187, vcc_lo, v171
	v_add_u32_e32 v188, vcc_lo, v172
	v_add_u32_e32 v189, vcc_lo, v173
	v_add_u32_e32 v190, vcc_lo, v174
	v_add_u32_e32 v191, vcc_lo, v175
	v_add_u32_e32 v192, vcc_lo, v176
	v_add_u32_e32 v193, vcc_lo, v177
	v_add_u32_e32 v194, vcc_lo, v178
	v_add_u32_e32 v195, vcc_lo, v179
	s_add_u32 s100, s12, 0x0
	s_addc_u32 s101, s13, 0
	s_add_u32 s0, s14, 0x0
	s_addc_u32 s1, s15, 0
	global_load_dwordx4 v[80:83], v154, s[100:101] offset:2048
	global_load_dwordx4 v[96:99], v158, s[0:1]
	global_load_dwordx4 v[84:87], v155, s[100:101] offset:2048
	global_load_dwordx4 v[100:103], v159, s[0:1]
	global_load_dwordx4 v[88:91], v156, s[100:101] offset:2048
	global_load_dwordx4 v[104:107], v160, s[0:1]
	global_load_dwordx4 v[92:95], v157, s[100:101] offset:2048
	global_load_dwordx4 v[108:111], v161, s[0:1]
	v_mov_b32_e32 v200, 0xf149f2ca
	v_mov_b32_e32 v201, 0
	v_mov_b32_e32 v32, 0
	v_mov_b32_e32 v33, 0
	v_mov_b32_e32 v34, 0
	v_mov_b32_e32 v35, 0
	v_mov_b32_e32 v36, 0
	v_mov_b32_e32 v37, 0
	v_mov_b32_e32 v38, 0
	v_mov_b32_e32 v39, 0
	v_mov_b32_e32 v40, 0
	v_mov_b32_e32 v41, 0
	v_mov_b32_e32 v42, 0
	v_mov_b32_e32 v43, 0
	v_mov_b32_e32 v44, 0
	v_mov_b32_e32 v45, 0
	v_mov_b32_e32 v46, 0
	v_mov_b32_e32 v47, 0
	s_waitcnt vmcnt(0)
	ds_write_b128 v150, v[80:83] offset:0
	ds_write_b128 v150, v[84:87] offset:4096
	ds_write_b128 v150, v[88:91] offset:8192
	ds_write_b128 v150, v[92:95] offset:12288
	ds_write_b64 v151, v[96:97] offset:0
	ds_write_b64 v229, v[98:99] offset:0
	ds_write_b64 v151, v[100:101] offset:4096
	ds_write_b64 v229, v[102:103] offset:4096
	ds_write_b64 v151, v[104:105] offset:8192
	ds_write_b64 v229, v[106:107] offset:8192
	ds_write_b64 v151, v[108:109] offset:12288
	ds_write_b64 v229, v[110:111] offset:12288
	s_add_u32 s100, s12, 0xc0000
	s_addc_u32 s101, s13, 0
	s_add_u32 s0, s14, 0x100
	s_addc_u32 s1, s15, 0
	global_load_dwordx4 v[80:83], v154, s[100:101] offset:2048
	global_load_dwordx4 v[96:99], v158, s[0:1]
	global_load_dwordx4 v[84:87], v155, s[100:101] offset:2048
	global_load_dwordx4 v[100:103], v159, s[0:1]
	global_load_dwordx4 v[88:91], v156, s[100:101] offset:2048
	global_load_dwordx4 v[104:107], v160, s[0:1]
	global_load_dwordx4 v[92:95], v157, s[100:101] offset:2048
	global_load_dwordx4 v[108:111], v161, s[0:1]
	s_waitcnt lgkmcnt(0)
	s_barrier
	ds_read_b32 v0, v184 offset:384
	ds_read_b32 v1, v185 offset:384
	ds_read_b32 v2, v186 offset:384
	ds_read_b32 v3, v187 offset:384
	ds_read_b32 v4, v184 offset:512
	ds_read_b32 v5, v185 offset:512
	ds_read_b32 v6, v186 offset:512
	ds_read_b32 v7, v187 offset:512
	ds_read_b32 v8, v188 offset:384
	ds_read_b32 v9, v189 offset:384
	ds_read_b32 v10, v190 offset:384
	ds_read_b32 v11, v191 offset:384
	ds_read_b32 v12, v188 offset:512
	ds_read_b32 v13, v189 offset:512
	ds_read_b32 v14, v190 offset:512
	ds_read_b32 v15, v191 offset:512
	ds_read_b32 v16, v192 offset:384
	ds_read_b32 v17, v193 offset:384
	ds_read_b32 v18, v194 offset:384
	ds_read_b32 v19, v195 offset:384
	ds_read_b32 v20, v192 offset:512
	ds_read_b32 v21, v193 offset:512
	ds_read_b32 v22, v194 offset:512
	ds_read_b32 v23, v195 offset:512
	s_waitcnt lgkmcnt(0)
	s_waitcnt vmcnt(0)
; __device__ __forceinline__ void attn_phase(const Params& P, char* smem_raw) {
;     ...
; #pragma unroll
;       for (int i = 0; i < 4; ++i) {
;         const int idx = tid + 256 * i;
;         *reinterpret_cast<uint4*>(&sm_k[(idx >> 3) * LDSS + (idx & 7) * 8]) = kreg[i];
;         *reinterpret_cast<uint4*>(&sm_vt[(idx >> 4) * 136 + (idx & 15) * 8]) = vreg[i];
;       }
;       __syncthreads();
;       f32x4 sacc[8];
; #pragma unroll
;       for (int t8 = 0; t8 < 8; ++t8) sacc[t8] = f32x4{0.f, 0.f, 0.f, 0.f};
; #pragma unroll
;       for (int s = 0; s < 2; ++s)
; #pragma unroll
;         for (int t8 = 0; t8 < 8; ++t8) {
;           const bf16x8 kf = *reinterpret_cast<const bf16x8*>(&sm_k[(t8 * 16 + (lane_c & 15)) * LDSS + s * 32 + (lane_c >> 4) * 8]);
;           sacc[t8] = __builtin_amdgcn_mfma_f32_16x16x32_bf16(qf[s], kf, sacc[t8], 0, 0, 0);
;         }
;       if (ck < 5) {
;         ATT_ISSUE(t, ck + 1)
;       } else if (t + VGRID < 8192) {
;         ATT_ISSUE(t + VGRID, 0)
;         ATT_QLOAD(t + VGRID)
;       }
;       if (ck < 4) {
;         const float* rb0 = sm_rpb + (rs + ck * 2 - r + 7) * 31;
; #pragma unroll
;         for (int t8 = 0; t8 < 8; ++t8)
; #pragma unroll
;           for (int reg = 0; reg < 4; ++reg)
;             sacc[t8][reg] += rb0[(t8 >> 2) * 31 + dco[reg][t8 & 3]];
;       }
; #pragma unroll
;       for (int reg = 0; reg < 4; ++reg) {
;         float mx = sacc[0][reg];
; #pragma unroll
;         for (int t8 = 1; t8 < 8; ++t8) mx = fmaxf(mx, sacc[t8][reg]);
;         mx = row16_max(mx);
;         const float mnew = fmaxf(mrow[reg], mx);
;         const float alpha = __builtin_amdgcn_exp2f(mrow[reg] - mnew);
;         mrow[reg] = mnew;
;         float rsum = 0.f;
; #pragma unroll
;         for (int t8 = 0; t8 < 8; ++t8) {
;           const float p = __builtin_amdgcn_exp2f(sacc[t8][reg] - mnew);
;           rsum += p;
;           sm_p[(wid * 16 + (lane_c >> 4) * 4 + reg) * 136 + t8 * 16 + (lane_c & 15)] = f2bf(p);
;         }
;         rsum = row16_sum(rsum);
;         lrow[reg] = lrow[reg] * alpha + rsum;
; #pragma unroll
;         for (int td = 0; td < 4; ++td) o[td][reg] *= alpha;
.Lmy_att_tile:
	s_barrier
	ds_read_b128 v[112:115], v144 offset:0
	ds_read_b128 v[116:119], v145 offset:0
	ds_read_b128 v[120:123], v144 offset:8192
	ds_read_b128 v[124:127], v145 offset:8192
	ds_read_b128 v[128:131], v144 offset:2048
	ds_read_b128 v[132:135], v145 offset:2048
	ds_read_b128 v[136:139], v144 offset:10240
	ds_read_b128 v[140:143], v145 offset:10240
	s_waitcnt lgkmcnt(7)
	v_mfma_f32_16x16x32_bf16 v[0:3], v[112:115], v[64:67], v[0:3]
	ds_read_b128 v[112:115], v144 offset:4096
	s_waitcnt lgkmcnt(7)
	v_mfma_f32_16x16x32_bf16 v[0:3], v[116:119], v[68:71], v[0:3]
	ds_read_b128 v[116:119], v145 offset:4096
	s_waitcnt lgkmcnt(7)
	v_mfma_f32_16x16x32_bf16 v[4:7], v[120:123], v[64:67], v[4:7]
	ds_read_b128 v[120:123], v144 offset:12288
	s_waitcnt lgkmcnt(7)
	v_mfma_f32_16x16x32_bf16 v[4:7], v[124:127], v[68:71], v[4:7]
	ds_read_b128 v[124:127], v145 offset:12288
	s_waitcnt lgkmcnt(7)
	v_mfma_f32_16x16x32_bf16 v[8:11], v[128:131], v[64:67], v[8:11]
	s_waitcnt lgkmcnt(6)
	v_mfma_f32_16x16x32_bf16 v[8:11], v[132:135], v[68:71], v[8:11]
	s_waitcnt lgkmcnt(5)
	v_mfma_f32_16x16x32_bf16 v[12:15], v[136:139], v[64:67], v[12:15]
	s_waitcnt lgkmcnt(4)
	v_mfma_f32_16x16x32_bf16 v[12:15], v[140:143], v[68:71], v[12:15]
	s_waitcnt lgkmcnt(3)
	v_mfma_f32_16x16x32_bf16 v[16:19], v[112:115], v[64:67], v[16:19]
	s_waitcnt lgkmcnt(2)
	v_mfma_f32_16x16x32_bf16 v[16:19], v[116:119], v[68:71], v[16:19]
	s_waitcnt lgkmcnt(1)
	v_mfma_f32_16x16x32_bf16 v[20:23], v[120:123], v[64:67], v[20:23]
	s_waitcnt lgkmcnt(0)
	v_mfma_f32_16x16x32_bf16 v[20:23], v[124:127], v[68:71], v[20:23]
	s_nop 7
	v_max3_f32 v203, v0, v1, v2
	v_max3_f32 v203, v203, v3, v4
	v_max3_f32 v203, v203, v5, v6
	v_max3_f32 v203, v203, v7, v8
	v_max3_f32 v203, v203, v9, v10
	v_max3_f32 v203, v203, v11, v12
	v_max3_f32 v203, v203, v13, v14
	v_max3_f32 v203, v203, v15, v16
	v_max3_f32 v203, v203, v17, v18
	v_max3_f32 v203, v203, v19, v20
	v_max3_f32 v203, v203, v21, v22
	v_max_f32_e32 v203, v203, v23
	v_mov_b32_e32 v205, v203
	s_nop 1
	v_permlane16_swap_b32_e32 v203, v205
	v_max_f32_e32 v203, v203, v205
	v_mov_b32_e32 v205, v203
	s_nop 1
	v_permlane32_swap_b32_e32 v203, v205
	v_max_f32_e32 v203, v203, v205
	v_max_f32_e32 v218, v200, v203
	v_sub_f32_e32 v220, v200, v218
	v_mov_b32_e32 v219, v218
	v_exp_f32_e32 v220, v220
	v_mov_b32_e32 v200, v218
	v_pk_add_f32 v[0:1], v[0:1], v[218:219] neg_lo:[0,1] neg_hi:[0,1]
	v_pk_add_f32 v[2:3], v[2:3], v[218:219] neg_lo:[0,1] neg_hi:[0,1]
	v_pk_add_f32 v[4:5], v[4:5], v[218:219] neg_lo:[0,1] neg_hi:[0,1]
	v_pk_add_f32 v[6:7], v[6:7], v[218:219] neg_lo:[0,1] neg_hi:[0,1]
	v_pk_add_f32 v[8:9], v[8:9], v[218:219] neg_lo:[0,1] neg_hi:[0,1]
	v_pk_add_f32 v[10:11], v[10:11], v[218:219] neg_lo:[0,1] neg_hi:[0,1]
	v_pk_add_f32 v[12:13], v[12:13], v[218:219] neg_lo:[0,1] neg_hi:[0,1]
	v_pk_add_f32 v[14:15], v[14:15], v[218:219] neg_lo:[0,1] neg_hi:[0,1]
	v_pk_add_f32 v[16:17], v[16:17], v[218:219] neg_lo:[0,1] neg_hi:[0,1]
	v_pk_add_f32 v[18:19], v[18:19], v[218:219] neg_lo:[0,1] neg_hi:[0,1]
	v_pk_add_f32 v[20:21], v[20:21], v[218:219] neg_lo:[0,1] neg_hi:[0,1]
	v_pk_add_f32 v[22:23], v[22:23], v[218:219] neg_lo:[0,1] neg_hi:[0,1]
	v_exp_f32_e32 v0, v0
	s_waitcnt vmcnt(4)
	v_exp_f32_e32 v1, v1
	ds_write_b128 v150, v[80:83] offset:32768
	v_exp_f32_e32 v2, v2
	ds_write_b128 v150, v[84:87] offset:36864
	v_exp_f32_e32 v3, v3
	ds_write_b128 v150, v[88:91] offset:40960
	v_exp_f32_e32 v4, v4
	ds_write_b128 v150, v[92:95] offset:45056
	v_exp_f32_e32 v5, v5
	ds_write_b64 v151, v[96:97] offset:32768
	v_exp_f32_e32 v6, v6
	ds_write_b64 v229, v[98:99] offset:32768
	v_exp_f32_e32 v7, v7
	ds_write_b64 v151, v[100:101] offset:36864
	v_exp_f32_e32 v8, v8
	ds_write_b64 v229, v[102:103] offset:36864
	v_exp_f32_e32 v9, v9
	ds_write_b64 v151, v[104:105] offset:40960
	v_exp_f32_e32 v10, v10
	ds_write_b64 v229, v[106:107] offset:40960
	v_exp_f32_e32 v11, v11
	ds_write_b64 v151, v[108:109] offset:45056
	v_exp_f32_e32 v12, v12
	ds_write_b64 v229, v[110:111] offset:45056
	v_exp_f32_e32 v13, v13
	s_add_u32 s100, s12, 0x180000
	v_exp_f32_e32 v14, v14
	s_addc_u32 s101, s13, 0
	v_exp_f32_e32 v15, v15
	s_add_u32 s0, s14, 0x200
	v_exp_f32_e32 v16, v16
	s_addc_u32 s1, s15, 0
	v_exp_f32_e32 v17, v17
	global_load_dwordx4 v[80:83], v154, s[100:101] offset:2048
	v_exp_f32_e32 v18, v18
	global_load_dwordx4 v[96:99], v158, s[0:1]
	v_exp_f32_e32 v19, v19
	global_load_dwordx4 v[84:87], v155, s[100:101] offset:2048
	v_exp_f32_e32 v20, v20
	global_load_dwordx4 v[100:103], v159, s[0:1]
	v_exp_f32_e32 v21, v21
	global_load_dwordx4 v[88:91], v156, s[100:101] offset:2048
	v_exp_f32_e32 v22, v22
	global_load_dwordx4 v[104:107], v160, s[0:1]
	v_exp_f32_e32 v23, v23
	global_load_dwordx4 v[92:95], v157, s[100:101] offset:2048
	global_load_dwordx4 v[108:111], v161, s[0:1]
	s_and_b32 s0, s3, 0xff
	s_lshr_b32 s1, s0, 2
	s_and_b32 s0, s0, 3
	s_lshl_b32 s0, s0, 5
	s_lshr_b32 vcc_lo, s3, 12
	s_add_u32 s0, s0, vcc_lo
	s_sub_i32 vcc_lo, s0, 4
	s_max_i32 vcc_lo, vcc_lo, 0
	s_min_i32 vcc_lo, vcc_lo, 0x78
	s_lshl_b32 vcc_hi, s1, 13
	s_lshl_b32 m0, s1, 8
	s_add_u32 m0, m0, 0x8000
	s_mul_i32 m0, m0, 0x1800
	s_add_u32 s16, s4, m0
	s_addc_u32 s17, s5, 0
	s_lshl_b32 m0, s1, 19
	s_add_u32 s36, s8, m0
	s_addc_u32 s37, s9, 0
	s_lshl_b32 m0, s0, 6
	s_add_u32 m0, m0, vcc_hi
	s_lshl_b32 m0, m0, 11
	s_add_u32 s98, s10, m0
	s_addc_u32 s99, s11, 0
	ds_read_b128 v[112:115], v146 offset:0
	ds_read_b128 v[116:119], v146 offset:4096
	ds_read_b128 v[120:123], v146 offset:8192
	ds_read_b128 v[124:127], v146 offset:12288
	ds_read_b128 v[128:131], v147 offset:0
	ds_read_b128 v[132:135], v147 offset:4096
	ds_read_b128 v[136:139], v147 offset:8192
; __device__ __forceinline__ void attn_phase(const Params& P, char* smem_raw) {
;     ...
;       if (ck < 4) {
;         const float* rb0 = sm_rpb + (rs + ck * 2 - r + 7) * 31;
; #pragma unroll
;         for (int t8 = 0; t8 < 8; ++t8)
; #pragma unroll
;           for (int reg = 0; reg < 4; ++reg)
;             sacc[t8][reg] += rb0[(t8 >> 2) * 31 + dco[reg][t8 & 3]];
;       }
; #pragma unroll
;       for (int reg = 0; reg < 4; ++reg) {
;         float mx = sacc[0][reg];
; #pragma unroll
;         for (int t8 = 1; t8 < 8; ++t8) mx = fmaxf(mx, sacc[t8][reg]);
;         mx = row16_max(mx);
;         const float mnew = fmaxf(mrow[reg], mx);
;         const float alpha = __builtin_amdgcn_exp2f(mrow[reg] - mnew);
;         mrow[reg] = mnew;
;         float rsum = 0.f;
; #pragma unroll
;         for (int t8 = 0; t8 < 8; ++t8) {
;           const float p = __builtin_amdgcn_exp2f(sacc[t8][reg] - mnew);
;           rsum += p;
;           sm_p[(wid * 16 + (lane_c >> 4) * 4 + reg) * 136 + t8 * 16 + (lane_c & 15)] = f2bf(p);
;         }
;         rsum = row16_sum(rsum);
;         lrow[reg] = lrow[reg] * alpha + rsum;
; #pragma unroll
;         for (int td = 0; td < 4; ++td) o[td][reg] *= alpha;
;       }
;       asm volatile("s_waitcnt lgkmcnt(0)" ::: "memory");
; #pragma unroll
;       for (int s4 = 0; s4 < 4; ++s4) {
;         const bf16x8 pf = *reinterpret_cast<const bf16x8*>(&sm_p[(wid * 16 + (lane_c & 15)) * 136 + s4 * 32 + (lane_c >> 4) * 8]);
; #pragma unroll
;         for (int td = 0; td < 4; ++td) {
;           const bf16x8 vf = *reinterpret_cast<const bf16x8*>(&sm_vt[(td * 16 + (lane_c & 15)) * 136 + s4 * 32 + (lane_c >> 4) * 8]);
;           o[td] = __builtin_amdgcn_mfma_f32_16x16x32_bf16(pf, vf, o[td], 0, 0, 0);
;         }
;       }
	ds_read_b128 v[140:143], v147 offset:12288
	v_mov_b32_e32 v221, v220
	v_pk_add_f32 v[222:223], v[0:1], v[2:3]
	v_pk_add_f32 v[222:223], v[222:223], v[4:5]
	v_pk_add_f32 v[222:223], v[222:223], v[6:7]
	v_pk_add_f32 v[222:223], v[222:223], v[8:9]
	v_pk_add_f32 v[222:223], v[222:223], v[10:11]
	v_pk_add_f32 v[222:223], v[222:223], v[12:13]
	v_pk_add_f32 v[222:223], v[222:223], v[14:15]
	v_pk_add_f32 v[222:223], v[222:223], v[16:17]
	v_pk_add_f32 v[222:223], v[222:223], v[18:19]
	v_pk_add_f32 v[222:223], v[222:223], v[20:21]
	v_pk_add_f32 v[222:223], v[222:223], v[22:23]
	v_pk_mul_f32 v[32:33], v[32:33], v[220:221]
	v_pk_mul_f32 v[34:35], v[34:35], v[220:221]
	v_pk_mul_f32 v[36:37], v[36:37], v[220:221]
	v_pk_mul_f32 v[38:39], v[38:39], v[220:221]
	v_pk_mul_f32 v[40:41], v[40:41], v[220:221]
	v_pk_mul_f32 v[42:43], v[42:43], v[220:221]
	v_pk_mul_f32 v[44:45], v[44:45], v[220:221]
	v_pk_mul_f32 v[46:47], v[46:47], v[220:221]
	v_add_f32_e32 v203, v222, v223
	v_fma_f32 v201, v201, v220, v203
	v_cvt_pk_bf16_f32 v48, v0, v1
	v_cvt_pk_bf16_f32 v49, v2, v3
	v_cvt_pk_bf16_f32 v50, v4, v5
	v_cvt_pk_bf16_f32 v51, v6, v7
	v_cvt_pk_bf16_f32 v52, v8, v9
	v_cvt_pk_bf16_f32 v53, v10, v11
	v_cvt_pk_bf16_f32 v54, v12, v13
	v_cvt_pk_bf16_f32 v55, v14, v15
	v_cvt_pk_bf16_f32 v56, v16, v17
	v_cvt_pk_bf16_f32 v57, v18, v19
	v_cvt_pk_bf16_f32 v58, v20, v21
	v_cvt_pk_bf16_f32 v59, v22, v23
	s_waitcnt lgkmcnt(7)
	v_mfma_f32_16x16x32_bf16 v[32:35], v[112:115], v[48:51], v[32:35]
	ds_read_b128 v[112:115], v148 offset:0
	s_waitcnt lgkmcnt(7)
	v_mfma_f32_16x16x32_bf16 v[36:39], v[116:119], v[48:51], v[36:39]
	ds_read_b128 v[116:119], v148 offset:4096
	s_waitcnt lgkmcnt(7)
	v_mfma_f32_16x16x32_bf16 v[40:43], v[120:123], v[48:51], v[40:43]
	ds_read_b128 v[120:123], v148 offset:8192
	s_waitcnt lgkmcnt(7)
	v_mfma_f32_16x16x32_bf16 v[44:47], v[124:127], v[48:51], v[44:47]
	ds_read_b128 v[124:127], v148 offset:12288
	s_waitcnt lgkmcnt(7)
	v_mfma_f32_16x16x32_bf16 v[32:35], v[128:131], v[52:55], v[32:35]
	s_waitcnt lgkmcnt(6)
	v_mfma_f32_16x16x32_bf16 v[36:39], v[132:135], v[52:55], v[36:39]
	s_waitcnt lgkmcnt(5)
	v_mfma_f32_16x16x32_bf16 v[40:43], v[136:139], v[52:55], v[40:43]
	s_waitcnt lgkmcnt(4)
	v_mfma_f32_16x16x32_bf16 v[44:47], v[140:143], v[52:55], v[44:47]
	s_waitcnt lgkmcnt(3)
	v_mfma_f32_16x16x32_bf16 v[32:35], v[112:115], v[56:59], v[32:35]
	s_waitcnt lgkmcnt(2)
	v_mfma_f32_16x16x32_bf16 v[36:39], v[116:119], v[56:59], v[36:39]
	s_waitcnt lgkmcnt(1)
	v_mfma_f32_16x16x32_bf16 v[40:43], v[120:123], v[56:59], v[40:43]
	s_waitcnt lgkmcnt(0)
	v_mfma_f32_16x16x32_bf16 v[44:47], v[124:127], v[56:59], v[44:47]
	ds_read_b32 v0, v184 offset:640
	ds_read_b32 v1, v185 offset:640
	ds_read_b32 v2, v186 offset:640
	ds_read_b32 v3, v187 offset:640
	ds_read_b32 v4, v184 offset:768
	ds_read_b32 v5, v185 offset:768
	ds_read_b32 v6, v186 offset:768
	ds_read_b32 v7, v187 offset:768
	ds_read_b32 v8, v188 offset:640
	ds_read_b32 v9, v189 offset:640
	ds_read_b32 v10, v190 offset:640
	ds_read_b32 v11, v191 offset:640
	ds_read_b32 v12, v188 offset:768
	ds_read_b32 v13, v189 offset:768
	ds_read_b32 v14, v190 offset:768
	ds_read_b32 v15, v191 offset:768
	ds_read_b32 v16, v192 offset:640
	ds_read_b32 v17, v193 offset:640
	ds_read_b32 v18, v194 offset:640
	ds_read_b32 v19, v195 offset:640
	ds_read_b32 v20, v192 offset:768
	ds_read_b32 v21, v193 offset:768
	ds_read_b32 v22, v194 offset:768
	ds_read_b32 v23, v195 offset:768
	s_waitcnt lgkmcnt(0)
	s_barrier
	ds_read_b128 v[112:115], v144 offset:32768
	ds_read_b128 v[116:119], v145 offset:32768
	ds_read_b128 v[120:123], v144 offset:40960
	ds_read_b128 v[124:127], v145 offset:40960
	ds_read_b128 v[128:131], v144 offset:34816
	ds_read_b128 v[132:135], v145 offset:34816
	ds_read_b128 v[136:139], v144 offset:43008
	ds_read_b128 v[140:143], v145 offset:43008
	s_waitcnt lgkmcnt(7)
	v_mfma_f32_16x16x32_bf16 v[0:3], v[112:115], v[64:67], v[0:3]
	ds_read_b128 v[112:115], v144 offset:36864
	s_waitcnt lgkmcnt(7)
	v_mfma_f32_16x16x32_bf16 v[0:3], v[116:119], v[68:71], v[0:3]
	ds_read_b128 v[116:119], v145 offset:36864
	s_waitcnt lgkmcnt(7)
	v_mfma_f32_16x16x32_bf16 v[4:7], v[120:123], v[64:67], v[4:7]
	ds_read_b128 v[120:123], v144 offset:45056
	s_waitcnt lgkmcnt(7)
	v_mfma_f32_16x16x32_bf16 v[4:7], v[124:127], v[68:71], v[4:7]
	ds_read_b128 v[124:127], v145 offset:45056
	s_waitcnt lgkmcnt(7)
	v_mfma_f32_16x16x32_bf16 v[8:11], v[128:131], v[64:67], v[8:11]
	s_waitcnt lgkmcnt(6)
	v_mfma_f32_16x16x32_bf16 v[8:11], v[132:135], v[68:71], v[8:11]
	s_waitcnt lgkmcnt(5)
	v_mfma_f32_16x16x32_bf16 v[12:15], v[136:139], v[64:67], v[12:15]
	s_waitcnt lgkmcnt(4)
	v_mfma_f32_16x16x32_bf16 v[12:15], v[140:143], v[68:71], v[12:15]
	s_waitcnt lgkmcnt(3)
	v_mfma_f32_16x16x32_bf16 v[16:19], v[112:115], v[64:67], v[16:19]
	s_waitcnt lgkmcnt(2)
	v_mfma_f32_16x16x32_bf16 v[16:19], v[116:119], v[68:71], v[16:19]
	s_waitcnt lgkmcnt(1)
	v_mfma_f32_16x16x32_bf16 v[20:23], v[120:123], v[64:67], v[20:23]
	s_waitcnt lgkmcnt(0)
; __device__ __forceinline__ void attn_phase(const Params& P, char* smem_raw) {
;     ...
;       if (ck < 5) {
;         ATT_ISSUE(t, ck + 1)
;       } else if (t + VGRID < 8192) {
;         ATT_ISSUE(t + VGRID, 0)
;         ATT_QLOAD(t + VGRID)
;       }
;       if (ck < 4) {
;         const float* rb0 = sm_rpb + (rs + ck * 2 - r + 7) * 31;
; #pragma unroll
;         for (int t8 = 0; t8 < 8; ++t8)
; #pragma unroll
;           for (int reg = 0; reg < 4; ++reg)
;             sacc[t8][reg] += rb0[(t8 >> 2) * 31 + dco[reg][t8 & 3]];
;       }
; #pragma unroll
;       for (int reg = 0; reg < 4; ++reg) {
;         float mx = sacc[0][reg];
; #pragma unroll
;         for (int t8 = 1; t8 < 8; ++t8) mx = fmaxf(mx, sacc[t8][reg]);
;         mx = row16_max(mx);
;         const float mnew = fmaxf(mrow[reg], mx);
;         const float alpha = __builtin_amdgcn_exp2f(mrow[reg] - mnew);
;         mrow[reg] = mnew;
;         float rsum = 0.f;
; #pragma unroll
;         for (int t8 = 0; t8 < 8; ++t8) {
;           const float p = __builtin_amdgcn_exp2f(sacc[t8][reg] - mnew);
;           rsum += p;
;           sm_p[(wid * 16 + (lane_c >> 4) * 4 + reg) * 136 + t8 * 16 + (lane_c & 15)] = f2bf(p);
;         }
;         rsum = row16_sum(rsum);
;         lrow[reg] = lrow[reg] * alpha + rsum;
; #pragma unroll
;         for (int td = 0; td < 4; ++td) o[td][reg] *= alpha;
;       }
;       asm volatile("s_waitcnt lgkmcnt(0)" ::: "memory");
; #pragma unroll
;       for (int s4 = 0; s4 < 4; ++s4) {
;         const bf16x8 pf = *reinterpret_cast<const bf16x8*>(&sm_p[(wid * 16 + (lane_c & 15)) * 136 + s4 * 32 + (lane_c >> 4) * 8]);
; #pragma unroll
;         for (int td = 0; td < 4; ++td) {
;           const bf16x8 vf = *reinterpret_cast<const bf16x8*>(&sm_vt[(td * 16 + (lane_c & 15)) * 136 + s4 * 32 + (lane_c >> 4) * 8]);
;           o[td] = __builtin_amdgcn_mfma_f32_16x16x32_bf16(pf, vf, o[td], 0, 0, 0);
;         }
;       }
	v_mfma_f32_16x16x32_bf16 v[20:23], v[124:127], v[68:71], v[20:23]
	s_nop 7
	v_max3_f32 v203, v0, v1, v2
	v_max3_f32 v203, v203, v3, v4
	v_max3_f32 v203, v203, v5, v6
	v_max3_f32 v203, v203, v7, v8
	v_max3_f32 v203, v203, v9, v10
	v_max3_f32 v203, v203, v11, v12
	v_max3_f32 v203, v203, v13, v14
	v_max3_f32 v203, v203, v15, v16
	v_max3_f32 v203, v203, v17, v18
	v_max3_f32 v203, v203, v19, v20
	v_max3_f32 v203, v203, v21, v22
	v_max_f32_e32 v203, v203, v23
	v_mov_b32_e32 v205, v203
	s_nop 1
	v_permlane16_swap_b32_e32 v203, v205
	v_max_f32_e32 v203, v203, v205
	v_mov_b32_e32 v205, v203
	s_nop 1
	v_permlane32_swap_b32_e32 v203, v205
	v_max_f32_e32 v203, v203, v205
	v_max_f32_e32 v218, v200, v203
	v_sub_f32_e32 v220, v200, v218
	v_mov_b32_e32 v219, v218
	v_exp_f32_e32 v220, v220
	v_mov_b32_e32 v200, v218
	v_pk_add_f32 v[0:1], v[0:1], v[218:219] neg_lo:[0,1] neg_hi:[0,1]
	v_pk_add_f32 v[2:3], v[2:3], v[218:219] neg_lo:[0,1] neg_hi:[0,1]
	v_pk_add_f32 v[4:5], v[4:5], v[218:219] neg_lo:[0,1] neg_hi:[0,1]
	v_pk_add_f32 v[6:7], v[6:7], v[218:219] neg_lo:[0,1] neg_hi:[0,1]
	v_pk_add_f32 v[8:9], v[8:9], v[218:219] neg_lo:[0,1] neg_hi:[0,1]
	v_pk_add_f32 v[10:11], v[10:11], v[218:219] neg_lo:[0,1] neg_hi:[0,1]
	v_pk_add_f32 v[12:13], v[12:13], v[218:219] neg_lo:[0,1] neg_hi:[0,1]
	v_pk_add_f32 v[14:15], v[14:15], v[218:219] neg_lo:[0,1] neg_hi:[0,1]
	v_pk_add_f32 v[16:17], v[16:17], v[218:219] neg_lo:[0,1] neg_hi:[0,1]
	v_pk_add_f32 v[18:19], v[18:19], v[218:219] neg_lo:[0,1] neg_hi:[0,1]
	v_pk_add_f32 v[20:21], v[20:21], v[218:219] neg_lo:[0,1] neg_hi:[0,1]
	v_pk_add_f32 v[22:23], v[22:23], v[218:219] neg_lo:[0,1] neg_hi:[0,1]
	v_exp_f32_e32 v0, v0
	s_waitcnt vmcnt(0)
	v_exp_f32_e32 v1, v1
	ds_write_b128 v150, v[80:83] offset:0
	v_exp_f32_e32 v2, v2
	ds_write_b128 v150, v[84:87] offset:4096
	v_exp_f32_e32 v3, v3
	ds_write_b128 v150, v[88:91] offset:8192
	v_exp_f32_e32 v4, v4
	ds_write_b128 v150, v[92:95] offset:12288
	v_exp_f32_e32 v5, v5
	ds_write_b64 v151, v[96:97] offset:0
	v_exp_f32_e32 v6, v6
	ds_write_b64 v229, v[98:99] offset:0
	v_exp_f32_e32 v7, v7
	ds_write_b64 v151, v[100:101] offset:4096
	v_exp_f32_e32 v8, v8
	ds_write_b64 v229, v[102:103] offset:4096
	v_exp_f32_e32 v9, v9
	ds_write_b64 v151, v[104:105] offset:8192
	v_exp_f32_e32 v10, v10
	ds_write_b64 v229, v[106:107] offset:8192
	v_exp_f32_e32 v11, v11
	ds_write_b64 v151, v[108:109] offset:12288
	v_exp_f32_e32 v12, v12
	ds_write_b64 v229, v[110:111] offset:12288
	v_exp_f32_e32 v13, v13
	s_add_u32 s100, s12, 0x240000
	v_exp_f32_e32 v14, v14
	s_addc_u32 s101, s13, 0
	v_exp_f32_e32 v15, v15
	s_add_u32 s0, s14, 0x300
	v_exp_f32_e32 v16, v16
	s_addc_u32 s1, s15, 0
	v_exp_f32_e32 v17, v17
	global_load_dwordx4 v[80:83], v154, s[100:101] offset:2048
	v_exp_f32_e32 v18, v18
	global_load_dwordx4 v[96:99], v158, s[0:1]
	v_exp_f32_e32 v19, v19
	global_load_dwordx4 v[84:87], v155, s[100:101] offset:2048
	v_exp_f32_e32 v20, v20
	global_load_dwordx4 v[100:103], v159, s[0:1]
	v_exp_f32_e32 v21, v21
	global_load_dwordx4 v[88:91], v156, s[100:101] offset:2048
	v_exp_f32_e32 v22, v22
	global_load_dwordx4 v[104:107], v160, s[0:1]
	v_exp_f32_e32 v23, v23
	global_load_dwordx4 v[92:95], v157, s[100:101] offset:2048
	global_load_dwordx4 v[108:111], v161, s[0:1]
	ds_read_b128 v[112:115], v146 offset:32768
	ds_read_b128 v[116:119], v146 offset:36864
	ds_read_b128 v[120:123], v146 offset:40960
	ds_read_b128 v[124:127], v146 offset:45056
	ds_read_b128 v[128:131], v147 offset:32768
	ds_read_b128 v[132:135], v147 offset:36864
	ds_read_b128 v[136:139], v147 offset:40960
	ds_read_b128 v[140:143], v147 offset:45056
	v_mov_b32_e32 v221, v220
	v_pk_add_f32 v[222:223], v[0:1], v[2:3]
	v_pk_add_f32 v[222:223], v[222:223], v[4:5]
	v_pk_add_f32 v[222:223], v[222:223], v[6:7]
	v_pk_add_f32 v[222:223], v[222:223], v[8:9]
	v_pk_add_f32 v[222:223], v[222:223], v[10:11]
	v_pk_add_f32 v[222:223], v[222:223], v[12:13]
	v_pk_add_f32 v[222:223], v[222:223], v[14:15]
	v_pk_add_f32 v[222:223], v[222:223], v[16:17]
	v_pk_add_f32 v[222:223], v[222:223], v[18:19]
	v_pk_add_f32 v[222:223], v[222:223], v[20:21]
	v_pk_add_f32 v[222:223], v[222:223], v[22:23]
	v_pk_mul_f32 v[32:33], v[32:33], v[220:221]
	v_pk_mul_f32 v[34:35], v[34:35], v[220:221]
	v_pk_mul_f32 v[36:37], v[36:37], v[220:221]
	v_pk_mul_f32 v[38:39], v[38:39], v[220:221]
	v_pk_mul_f32 v[40:41], v[40:41], v[220:221]
	v_pk_mul_f32 v[42:43], v[42:43], v[220:221]
	v_pk_mul_f32 v[44:45], v[44:45], v[220:221]
	v_pk_mul_f32 v[46:47], v[46:47], v[220:221]
	v_add_f32_e32 v203, v222, v223
	v_fma_f32 v201, v201, v220, v203
	v_cvt_pk_bf16_f32 v48, v0, v1
	v_cvt_pk_bf16_f32 v49, v2, v3
	v_cvt_pk_bf16_f32 v50, v4, v5
	v_cvt_pk_bf16_f32 v51, v6, v7
	v_cvt_pk_bf16_f32 v52, v8, v9
	v_cvt_pk_bf16_f32 v53, v10, v11
	v_cvt_pk_bf16_f32 v54, v12, v13
	v_cvt_pk_bf16_f32 v55, v14, v15
	v_cvt_pk_bf16_f32 v56, v16, v17
	v_cvt_pk_bf16_f32 v57, v18, v19
	v_cvt_pk_bf16_f32 v58, v20, v21
	v_cvt_pk_bf16_f32 v59, v22, v23
	s_waitcnt lgkmcnt(7)
	v_mfma_f32_16x16x32_bf16 v[32:35], v[112:115], v[48:51], v[32:35]
	ds_read_b128 v[112:115], v148 offset:32768
	s_waitcnt lgkmcnt(7)
	v_mfma_f32_16x16x32_bf16 v[36:39], v[116:119], v[48:51], v[36:39]
	ds_read_b128 v[116:119], v148 offset:36864
	s_waitcnt lgkmcnt(7)
	v_mfma_f32_16x16x32_bf16 v[40:43], v[120:123], v[48:51], v[40:43]
	ds_read_b128 v[120:123], v148 offset:40960
	s_waitcnt lgkmcnt(7)
	v_mfma_f32_16x16x32_bf16 v[44:47], v[124:127], v[48:51], v[44:47]
	ds_read_b128 v[124:127], v148 offset:45056
	s_waitcnt lgkmcnt(7)
	v_mfma_f32_16x16x32_bf16 v[32:35], v[128:131], v[52:55], v[32:35]
	s_waitcnt lgkmcnt(6)
	v_mfma_f32_16x16x32_bf16 v[36:39], v[132:135], v[52:55], v[36:39]
	s_waitcnt lgkmcnt(5)
	v_mfma_f32_16x16x32_bf16 v[40:43], v[136:139], v[52:55], v[40:43]
	s_waitcnt lgkmcnt(4)
	v_mfma_f32_16x16x32_bf16 v[44:47], v[140:143], v[52:55], v[44:47]
	s_waitcnt lgkmcnt(3)
	v_mfma_f32_16x16x32_bf16 v[32:35], v[112:115], v[56:59], v[32:35]
	s_waitcnt lgkmcnt(2)
	v_mfma_f32_16x16x32_bf16 v[36:39], v[116:119], v[56:59], v[36:39]
	s_waitcnt lgkmcnt(1)
	v_mfma_f32_16x16x32_bf16 v[40:43], v[120:123], v[56:59], v[40:43]
	s_waitcnt lgkmcnt(0)
	v_mfma_f32_16x16x32_bf16 v[44:47], v[124:127], v[56:59], v[44:47]
	ds_read_b32 v0, v184 offset:896
	ds_read_b32 v1, v185 offset:896
	ds_read_b32 v2, v186 offset:896
	ds_read_b32 v3, v187 offset:896
	ds_read_b32 v4, v184 offset:1024
	ds_read_b32 v5, v185 offset:1024
	ds_read_b32 v6, v186 offset:1024
	ds_read_b32 v7, v187 offset:1024
	ds_read_b32 v8, v188 offset:896
	ds_read_b32 v9, v189 offset:896
	ds_read_b32 v10, v190 offset:896
	ds_read_b32 v11, v191 offset:896
	ds_read_b32 v12, v188 offset:1024
	ds_read_b32 v13, v189 offset:1024
	ds_read_b32 v14, v190 offset:1024
	ds_read_b32 v15, v191 offset:1024
	ds_read_b32 v16, v192 offset:896
	ds_read_b32 v17, v193 offset:896
	ds_read_b32 v18, v194 offset:896
	ds_read_b32 v19, v195 offset:896
	ds_read_b32 v20, v192 offset:1024
	ds_read_b32 v21, v193 offset:1024
	ds_read_b32 v22, v194 offset:1024
	ds_read_b32 v23, v195 offset:1024
	s_waitcnt lgkmcnt(0)
	s_barrier
; __device__ __forceinline__ void attn_phase(const Params& P, char* smem_raw) {
;     ...
;       for (int s = 0; s < 2; ++s)
; #pragma unroll
;         for (int t8 = 0; t8 < 8; ++t8) {
;           const bf16x8 kf = *reinterpret_cast<const bf16x8*>(&sm_k[(t8 * 16 + (lane_c & 15)) * LDSS + s * 32 + (lane_c >> 4) * 8]);
;           sacc[t8] = __builtin_amdgcn_mfma_f32_16x16x32_bf16(qf[s], kf, sacc[t8], 0, 0, 0);
;         }
;       if (ck < 5) {
;         ATT_ISSUE(t, ck + 1)
;       } else if (t + VGRID < 8192) {
;         ATT_ISSUE(t + VGRID, 0)
;         ATT_QLOAD(t + VGRID)
;       }
;       if (ck < 4) {
;         const float* rb0 = sm_rpb + (rs + ck * 2 - r + 7) * 31;
; #pragma unroll
;         for (int t8 = 0; t8 < 8; ++t8)
; #pragma unroll
;           for (int reg = 0; reg < 4; ++reg)
;             sacc[t8][reg] += rb0[(t8 >> 2) * 31 + dco[reg][t8 & 3]];
;       }
; #pragma unroll
;       for (int reg = 0; reg < 4; ++reg) {
;         float mx = sacc[0][reg];
; #pragma unroll
;         for (int t8 = 1; t8 < 8; ++t8) mx = fmaxf(mx, sacc[t8][reg]);
;         mx = row16_max(mx);
;         const float mnew = fmaxf(mrow[reg], mx);
;         const float alpha = __builtin_amdgcn_exp2f(mrow[reg] - mnew);
;         mrow[reg] = mnew;
;         float rsum = 0.f;
; #pragma unroll
;         for (int t8 = 0; t8 < 8; ++t8) {
;           const float p = __builtin_amdgcn_exp2f(sacc[t8][reg] - mnew);
;           rsum += p;
;           sm_p[(wid * 16 + (lane_c >> 4) * 4 + reg) * 136 + t8 * 16 + (lane_c & 15)] = f2bf(p);
;         }
;         rsum = row16_sum(rsum);
;         lrow[reg] = lrow[reg] * alpha + rsum;
; #pragma unroll
;         for (int td = 0; td < 4; ++td) o[td][reg] *= alpha;
;       }
;       asm volatile("s_waitcnt lgkmcnt(0)" ::: "memory");
; #pragma unroll
;       for (int s4 = 0; s4 < 4; ++s4) {
;         const bf16x8 pf = *reinterpret_cast<const bf16x8*>(&sm_p[(wid * 16 + (lane_c & 15)) * 136 + s4 * 32 + (lane_c >> 4) * 8]);
; #pragma unroll
;         for (int td = 0; td < 4; ++td) {
;           const bf16x8 vf = *reinterpret_cast<const bf16x8*>(&sm_vt[(td * 16 + (lane_c & 15)) * 136 + s4 * 32 + (lane_c >> 4) * 8]);
;           o[td] = __builtin_amdgcn_mfma_f32_16x16x32_bf16(pf, vf, o[td], 0, 0, 0);
;         }
;       }
	ds_read_b128 v[112:115], v144 offset:0
	ds_read_b128 v[116:119], v145 offset:0
	ds_read_b128 v[120:123], v144 offset:8192
	ds_read_b128 v[124:127], v145 offset:8192
	ds_read_b128 v[128:131], v144 offset:2048
	ds_read_b128 v[132:135], v145 offset:2048
	ds_read_b128 v[136:139], v144 offset:10240
	ds_read_b128 v[140:143], v145 offset:10240
	s_waitcnt lgkmcnt(7)
	v_mfma_f32_16x16x32_bf16 v[0:3], v[112:115], v[64:67], v[0:3]
	ds_read_b128 v[112:115], v144 offset:4096
	s_waitcnt lgkmcnt(7)
	v_mfma_f32_16x16x32_bf16 v[0:3], v[116:119], v[68:71], v[0:3]
	ds_read_b128 v[116:119], v145 offset:4096
	s_waitcnt lgkmcnt(7)
	v_mfma_f32_16x16x32_bf16 v[4:7], v[120:123], v[64:67], v[4:7]
	ds_read_b128 v[120:123], v144 offset:12288
	s_waitcnt lgkmcnt(7)
	v_mfma_f32_16x16x32_bf16 v[4:7], v[124:127], v[68:71], v[4:7]
	ds_read_b128 v[124:127], v145 offset:12288
	s_waitcnt lgkmcnt(7)
	v_mfma_f32_16x16x32_bf16 v[8:11], v[128:131], v[64:67], v[8:11]
	s_waitcnt lgkmcnt(6)
	v_mfma_f32_16x16x32_bf16 v[8:11], v[132:135], v[68:71], v[8:11]
	s_waitcnt lgkmcnt(5)
	v_mfma_f32_16x16x32_bf16 v[12:15], v[136:139], v[64:67], v[12:15]
	s_waitcnt lgkmcnt(4)
	v_mfma_f32_16x16x32_bf16 v[12:15], v[140:143], v[68:71], v[12:15]
	s_waitcnt lgkmcnt(3)
	v_mfma_f32_16x16x32_bf16 v[16:19], v[112:115], v[64:67], v[16:19]
	s_waitcnt lgkmcnt(2)
	v_mfma_f32_16x16x32_bf16 v[16:19], v[116:119], v[68:71], v[16:19]
	s_waitcnt lgkmcnt(1)
	v_mfma_f32_16x16x32_bf16 v[20:23], v[120:123], v[64:67], v[20:23]
	s_waitcnt lgkmcnt(0)
	v_mfma_f32_16x16x32_bf16 v[20:23], v[124:127], v[68:71], v[20:23]
	s_nop 7
	v_max3_f32 v203, v0, v1, v2
	v_max3_f32 v203, v203, v3, v4
	v_max3_f32 v203, v203, v5, v6
	v_max3_f32 v203, v203, v7, v8
	v_max3_f32 v203, v203, v9, v10
	v_max3_f32 v203, v203, v11, v12
	v_max3_f32 v203, v203, v13, v14
	v_max3_f32 v203, v203, v15, v16
	v_max3_f32 v203, v203, v17, v18
	v_max3_f32 v203, v203, v19, v20
	v_max3_f32 v203, v203, v21, v22
	v_max_f32_e32 v203, v203, v23
	v_mov_b32_e32 v205, v203
	s_nop 1
	v_permlane16_swap_b32_e32 v203, v205
	v_max_f32_e32 v203, v203, v205
	v_mov_b32_e32 v205, v203
	s_nop 1
	v_permlane32_swap_b32_e32 v203, v205
	v_max_f32_e32 v203, v203, v205
	v_max_f32_e32 v218, v200, v203
	v_sub_f32_e32 v220, v200, v218
	v_mov_b32_e32 v219, v218
	v_exp_f32_e32 v220, v220
	v_mov_b32_e32 v200, v218
	v_pk_add_f32 v[0:1], v[0:1], v[218:219] neg_lo:[0,1] neg_hi:[0,1]
	v_pk_add_f32 v[2:3], v[2:3], v[218:219] neg_lo:[0,1] neg_hi:[0,1]
	v_pk_add_f32 v[4:5], v[4:5], v[218:219] neg_lo:[0,1] neg_hi:[0,1]
	v_pk_add_f32 v[6:7], v[6:7], v[218:219] neg_lo:[0,1] neg_hi:[0,1]
	v_pk_add_f32 v[8:9], v[8:9], v[218:219] neg_lo:[0,1] neg_hi:[0,1]
	v_pk_add_f32 v[10:11], v[10:11], v[218:219] neg_lo:[0,1] neg_hi:[0,1]
	v_pk_add_f32 v[12:13], v[12:13], v[218:219] neg_lo:[0,1] neg_hi:[0,1]
	v_pk_add_f32 v[14:15], v[14:15], v[218:219] neg_lo:[0,1] neg_hi:[0,1]
	v_pk_add_f32 v[16:17], v[16:17], v[218:219] neg_lo:[0,1] neg_hi:[0,1]
	v_pk_add_f32 v[18:19], v[18:19], v[218:219] neg_lo:[0,1] neg_hi:[0,1]
	v_pk_add_f32 v[20:21], v[20:21], v[218:219] neg_lo:[0,1] neg_hi:[0,1]
	v_pk_add_f32 v[22:23], v[22:23], v[218:219] neg_lo:[0,1] neg_hi:[0,1]
	v_exp_f32_e32 v0, v0
	s_waitcnt vmcnt(0)
	v_exp_f32_e32 v1, v1
	ds_write_b128 v150, v[80:83] offset:32768
	v_exp_f32_e32 v2, v2
	ds_write_b128 v150, v[84:87] offset:36864
	v_exp_f32_e32 v3, v3
	ds_write_b128 v150, v[88:91] offset:40960
	v_exp_f32_e32 v4, v4
	ds_write_b128 v150, v[92:95] offset:45056
	v_exp_f32_e32 v5, v5
	ds_write_b64 v151, v[96:97] offset:32768
	v_exp_f32_e32 v6, v6
	ds_write_b64 v229, v[98:99] offset:32768
	v_exp_f32_e32 v7, v7
	ds_write_b64 v151, v[100:101] offset:36864
	v_exp_f32_e32 v8, v8
	ds_write_b64 v229, v[102:103] offset:36864
	v_exp_f32_e32 v9, v9
	ds_write_b64 v151, v[104:105] offset:40960
	v_exp_f32_e32 v10, v10
	ds_write_b64 v229, v[106:107] offset:40960
	v_exp_f32_e32 v11, v11
	ds_write_b64 v151, v[108:109] offset:45056
	v_exp_f32_e32 v12, v12
	ds_write_b64 v229, v[110:111] offset:45056
	v_exp_f32_e32 v13, v13
	s_add_u32 s100, s16, 0x0
	v_exp_f32_e32 v14, v14
	s_addc_u32 s101, s17, 0
	v_exp_f32_e32 v15, v15
	s_add_u32 s0, s36, 0x0
	v_exp_f32_e32 v16, v16
	s_addc_u32 s1, s37, 0
	v_exp_f32_e32 v17, v17
	global_load_dwordx4 v[80:83], v154, s[100:101] offset:2048
	v_exp_f32_e32 v18, v18
	global_load_dwordx4 v[96:99], v162, s[0:1]
	v_exp_f32_e32 v19, v19
	global_load_dwordx4 v[84:87], v155, s[100:101] offset:2048
	v_exp_f32_e32 v20, v20
	global_load_dwordx4 v[100:103], v163, s[0:1]
	v_exp_f32_e32 v21, v21
	global_load_dwordx4 v[88:91], v156, s[100:101] offset:2048
	v_exp_f32_e32 v22, v22
	global_load_dwordx4 v[104:107], v164, s[0:1]
	v_exp_f32_e32 v23, v23
	global_load_dwordx4 v[92:95], v157, s[100:101] offset:2048
	global_load_dwordx4 v[108:111], v165, s[0:1]
	ds_read_b128 v[112:115], v146 offset:0
	ds_read_b128 v[116:119], v146 offset:4096
	ds_read_b128 v[120:123], v146 offset:8192
	ds_read_b128 v[124:127], v146 offset:12288
	ds_read_b128 v[128:131], v147 offset:0
	ds_read_b128 v[132:135], v147 offset:4096
	ds_read_b128 v[136:139], v147 offset:8192
	ds_read_b128 v[140:143], v147 offset:12288
	v_mov_b32_e32 v221, v220
	v_pk_add_f32 v[222:223], v[0:1], v[2:3]
	v_pk_add_f32 v[222:223], v[222:223], v[4:5]
	v_pk_add_f32 v[222:223], v[222:223], v[6:7]
	v_pk_add_f32 v[222:223], v[222:223], v[8:9]
	v_pk_add_f32 v[222:223], v[222:223], v[10:11]
	v_pk_add_f32 v[222:223], v[222:223], v[12:13]
	v_pk_add_f32 v[222:223], v[222:223], v[14:15]
	v_pk_add_f32 v[222:223], v[222:223], v[16:17]
	v_pk_add_f32 v[222:223], v[222:223], v[18:19]
	v_pk_add_f32 v[222:223], v[222:223], v[20:21]
	v_pk_add_f32 v[222:223], v[222:223], v[22:23]
	v_pk_mul_f32 v[32:33], v[32:33], v[220:221]
	v_pk_mul_f32 v[34:35], v[34:35], v[220:221]
	v_pk_mul_f32 v[36:37], v[36:37], v[220:221]
	v_pk_mul_f32 v[38:39], v[38:39], v[220:221]
	v_pk_mul_f32 v[40:41], v[40:41], v[220:221]
	v_pk_mul_f32 v[42:43], v[42:43], v[220:221]
	v_pk_mul_f32 v[44:45], v[44:45], v[220:221]
	v_pk_mul_f32 v[46:47], v[46:47], v[220:221]
	v_add_f32_e32 v203, v222, v223
	v_fma_f32 v201, v201, v220, v203
	v_cvt_pk_bf16_f32 v48, v0, v1
	v_cvt_pk_bf16_f32 v49, v2, v3
	v_cvt_pk_bf16_f32 v50, v4, v5
	v_cvt_pk_bf16_f32 v51, v6, v7
	v_cvt_pk_bf16_f32 v52, v8, v9
	v_cvt_pk_bf16_f32 v53, v10, v11
	v_cvt_pk_bf16_f32 v54, v12, v13
	v_cvt_pk_bf16_f32 v55, v14, v15
	v_cvt_pk_bf16_f32 v56, v16, v17
	v_cvt_pk_bf16_f32 v57, v18, v19
	v_cvt_pk_bf16_f32 v58, v20, v21
	v_cvt_pk_bf16_f32 v59, v22, v23
	s_waitcnt lgkmcnt(7)
; __device__ __forceinline__ void attn_phase(const Params& P, char* smem_raw) {
;     ...
;       if (ck < 4) {
;         const float* rb0 = sm_rpb + (rs + ck * 2 - r + 7) * 31;
; #pragma unroll
;         for (int t8 = 0; t8 < 8; ++t8)
; #pragma unroll
;           for (int reg = 0; reg < 4; ++reg)
;             sacc[t8][reg] += rb0[(t8 >> 2) * 31 + dco[reg][t8 & 3]];
;       }
; #pragma unroll
;       for (int reg = 0; reg < 4; ++reg) {
;         float mx = sacc[0][reg];
; #pragma unroll
;         for (int t8 = 1; t8 < 8; ++t8) mx = fmaxf(mx, sacc[t8][reg]);
;         mx = row16_max(mx);
;         const float mnew = fmaxf(mrow[reg], mx);
;         const float alpha = __builtin_amdgcn_exp2f(mrow[reg] - mnew);
;         mrow[reg] = mnew;
;         float rsum = 0.f;
; #pragma unroll
;         for (int t8 = 0; t8 < 8; ++t8) {
;           const float p = __builtin_amdgcn_exp2f(sacc[t8][reg] - mnew);
;           rsum += p;
;           sm_p[(wid * 16 + (lane_c >> 4) * 4 + reg) * 136 + t8 * 16 + (lane_c & 15)] = f2bf(p);
;         }
;         rsum = row16_sum(rsum);
;         lrow[reg] = lrow[reg] * alpha + rsum;
; #pragma unroll
;         for (int td = 0; td < 4; ++td) o[td][reg] *= alpha;
;       }
;       asm volatile("s_waitcnt lgkmcnt(0)" ::: "memory");
; #pragma unroll
;       for (int s4 = 0; s4 < 4; ++s4) {
;         const bf16x8 pf = *reinterpret_cast<const bf16x8*>(&sm_p[(wid * 16 + (lane_c & 15)) * 136 + s4 * 32 + (lane_c >> 4) * 8]);
; #pragma unroll
;         for (int td = 0; td < 4; ++td) {
;           const bf16x8 vf = *reinterpret_cast<const bf16x8*>(&sm_vt[(td * 16 + (lane_c & 15)) * 136 + s4 * 32 + (lane_c >> 4) * 8]);
;           o[td] = __builtin_amdgcn_mfma_f32_16x16x32_bf16(pf, vf, o[td], 0, 0, 0);
;         }
;       }
	v_mfma_f32_16x16x32_bf16 v[32:35], v[112:115], v[48:51], v[32:35]
	ds_read_b128 v[112:115], v148 offset:0
	s_waitcnt lgkmcnt(7)
	v_mfma_f32_16x16x32_bf16 v[36:39], v[116:119], v[48:51], v[36:39]
	ds_read_b128 v[116:119], v148 offset:4096
	s_waitcnt lgkmcnt(7)
	v_mfma_f32_16x16x32_bf16 v[40:43], v[120:123], v[48:51], v[40:43]
	ds_read_b128 v[120:123], v148 offset:8192
	s_waitcnt lgkmcnt(7)
	v_mfma_f32_16x16x32_bf16 v[44:47], v[124:127], v[48:51], v[44:47]
	ds_read_b128 v[124:127], v148 offset:12288
	s_waitcnt lgkmcnt(7)
	v_mfma_f32_16x16x32_bf16 v[32:35], v[128:131], v[52:55], v[32:35]
	s_waitcnt lgkmcnt(6)
	v_mfma_f32_16x16x32_bf16 v[36:39], v[132:135], v[52:55], v[36:39]
	s_waitcnt lgkmcnt(5)
	v_mfma_f32_16x16x32_bf16 v[40:43], v[136:139], v[52:55], v[40:43]
	s_waitcnt lgkmcnt(4)
	v_mfma_f32_16x16x32_bf16 v[44:47], v[140:143], v[52:55], v[44:47]
	s_waitcnt lgkmcnt(3)
	v_mfma_f32_16x16x32_bf16 v[32:35], v[112:115], v[56:59], v[32:35]
	s_waitcnt lgkmcnt(2)
	v_mfma_f32_16x16x32_bf16 v[36:39], v[116:119], v[56:59], v[36:39]
	s_waitcnt lgkmcnt(1)
	v_mfma_f32_16x16x32_bf16 v[40:43], v[120:123], v[56:59], v[40:43]
	s_waitcnt lgkmcnt(0)
	v_mfma_f32_16x16x32_bf16 v[44:47], v[124:127], v[56:59], v[44:47]
	ds_read_b32 v0, v184 offset:1152
	ds_read_b32 v1, v185 offset:1152
	ds_read_b32 v2, v186 offset:1152
	ds_read_b32 v3, v187 offset:1152
	ds_read_b32 v4, v184 offset:1280
	ds_read_b32 v5, v185 offset:1280
	ds_read_b32 v6, v186 offset:1280
	ds_read_b32 v7, v187 offset:1280
	ds_read_b32 v8, v188 offset:1152
	ds_read_b32 v9, v189 offset:1152
	ds_read_b32 v10, v190 offset:1152
	ds_read_b32 v11, v191 offset:1152
	ds_read_b32 v12, v188 offset:1280
	ds_read_b32 v13, v189 offset:1280
	ds_read_b32 v14, v190 offset:1280
	ds_read_b32 v15, v191 offset:1280
	ds_read_b32 v16, v192 offset:1152
	ds_read_b32 v17, v193 offset:1152
	ds_read_b32 v18, v194 offset:1152
	ds_read_b32 v19, v195 offset:1152
	ds_read_b32 v20, v192 offset:1280
	ds_read_b32 v21, v193 offset:1280
	ds_read_b32 v22, v194 offset:1280
	ds_read_b32 v23, v195 offset:1280
	s_waitcnt lgkmcnt(0)
	s_barrier
	ds_read_b128 v[112:115], v144 offset:32768
	ds_read_b128 v[116:119], v145 offset:32768
	ds_read_b128 v[120:123], v144 offset:40960
	ds_read_b128 v[124:127], v145 offset:40960
	ds_read_b128 v[128:131], v144 offset:34816
	ds_read_b128 v[132:135], v145 offset:34816
	ds_read_b128 v[136:139], v144 offset:43008
	ds_read_b128 v[140:143], v145 offset:43008
	s_waitcnt lgkmcnt(7)
	v_mfma_f32_16x16x32_bf16 v[0:3], v[112:115], v[64:67], v[0:3]
	ds_read_b128 v[112:115], v144 offset:36864
	s_waitcnt lgkmcnt(7)
	v_mfma_f32_16x16x32_bf16 v[0:3], v[116:119], v[68:71], v[0:3]
	ds_read_b128 v[116:119], v145 offset:36864
	s_waitcnt lgkmcnt(7)
	v_mfma_f32_16x16x32_bf16 v[4:7], v[120:123], v[64:67], v[4:7]
	ds_read_b128 v[120:123], v144 offset:45056
	s_waitcnt lgkmcnt(7)
	v_mfma_f32_16x16x32_bf16 v[4:7], v[124:127], v[68:71], v[4:7]
	ds_read_b128 v[124:127], v145 offset:45056
	s_waitcnt lgkmcnt(7)
	v_mfma_f32_16x16x32_bf16 v[8:11], v[128:131], v[64:67], v[8:11]
	s_waitcnt lgkmcnt(6)
	v_mfma_f32_16x16x32_bf16 v[8:11], v[132:135], v[68:71], v[8:11]
	s_waitcnt lgkmcnt(5)
	v_mfma_f32_16x16x32_bf16 v[12:15], v[136:139], v[64:67], v[12:15]
	s_waitcnt lgkmcnt(4)
	v_mfma_f32_16x16x32_bf16 v[12:15], v[140:143], v[68:71], v[12:15]
	s_waitcnt lgkmcnt(3)
	v_mfma_f32_16x16x32_bf16 v[16:19], v[112:115], v[64:67], v[16:19]
	s_waitcnt lgkmcnt(2)
	v_mfma_f32_16x16x32_bf16 v[16:19], v[116:119], v[68:71], v[16:19]
	s_waitcnt lgkmcnt(1)
	v_mfma_f32_16x16x32_bf16 v[20:23], v[120:123], v[64:67], v[20:23]
	s_waitcnt lgkmcnt(0)
	v_mfma_f32_16x16x32_bf16 v[20:23], v[124:127], v[68:71], v[20:23]
	s_nop 7
	v_max3_f32 v203, v0, v1, v2
	v_max3_f32 v203, v203, v3, v4
	v_max3_f32 v203, v203, v5, v6
	v_max3_f32 v203, v203, v7, v8
	v_max3_f32 v203, v203, v9, v10
	v_max3_f32 v203, v203, v11, v12
	v_max3_f32 v203, v203, v13, v14
	v_max3_f32 v203, v203, v15, v16
	v_max3_f32 v203, v203, v17, v18
	v_max3_f32 v203, v203, v19, v20
	v_max3_f32 v203, v203, v21, v22
	v_max_f32_e32 v203, v203, v23
	v_mov_b32_e32 v205, v203
	s_nop 1
	v_permlane16_swap_b32_e32 v203, v205
	v_max_f32_e32 v203, v203, v205
	v_mov_b32_e32 v205, v203
	s_nop 1
	v_permlane32_swap_b32_e32 v203, v205
	v_max_f32_e32 v203, v203, v205
	v_max_f32_e32 v218, v200, v203
	v_sub_f32_e32 v220, v200, v218
	v_mov_b32_e32 v219, v218
	v_exp_f32_e32 v220, v220
	v_mov_b32_e32 v200, v218
	v_pk_add_f32 v[0:1], v[0:1], v[218:219] neg_lo:[0,1] neg_hi:[0,1]
	v_pk_add_f32 v[2:3], v[2:3], v[218:219] neg_lo:[0,1] neg_hi:[0,1]
	v_pk_add_f32 v[4:5], v[4:5], v[218:219] neg_lo:[0,1] neg_hi:[0,1]
	v_pk_add_f32 v[6:7], v[6:7], v[218:219] neg_lo:[0,1] neg_hi:[0,1]
	v_pk_add_f32 v[8:9], v[8:9], v[218:219] neg_lo:[0,1] neg_hi:[0,1]
	v_pk_add_f32 v[10:11], v[10:11], v[218:219] neg_lo:[0,1] neg_hi:[0,1]
	v_pk_add_f32 v[12:13], v[12:13], v[218:219] neg_lo:[0,1] neg_hi:[0,1]
	v_pk_add_f32 v[14:15], v[14:15], v[218:219] neg_lo:[0,1] neg_hi:[0,1]
	v_pk_add_f32 v[16:17], v[16:17], v[218:219] neg_lo:[0,1] neg_hi:[0,1]
	v_pk_add_f32 v[18:19], v[18:19], v[218:219] neg_lo:[0,1] neg_hi:[0,1]
	v_pk_add_f32 v[20:21], v[20:21], v[218:219] neg_lo:[0,1] neg_hi:[0,1]
	v_pk_add_f32 v[22:23], v[22:23], v[218:219] neg_lo:[0,1] neg_hi:[0,1]
	v_exp_f32_e32 v0, v0
	s_waitcnt vmcnt(0)
; __device__ __forceinline__ void attn_phase(const Params& P, char* smem_raw) {
;     ...
;       if (ck < 5) {
;         ATT_ISSUE(t, ck + 1)
;       } else if (t + VGRID < 8192) {
;         ATT_ISSUE(t + VGRID, 0)
;         ATT_QLOAD(t + VGRID)
;       }
;       if (ck < 4) {
;         const float* rb0 = sm_rpb + (rs + ck * 2 - r + 7) * 31;
; #pragma unroll
;         for (int t8 = 0; t8 < 8; ++t8)
; #pragma unroll
;           for (int reg = 0; reg < 4; ++reg)
;             sacc[t8][reg] += rb0[(t8 >> 2) * 31 + dco[reg][t8 & 3]];
;       }
; #pragma unroll
;       for (int reg = 0; reg < 4; ++reg) {
;         float mx = sacc[0][reg];
; #pragma unroll
;         for (int t8 = 1; t8 < 8; ++t8) mx = fmaxf(mx, sacc[t8][reg]);
;         mx = row16_max(mx);
;         const float mnew = fmaxf(mrow[reg], mx);
;         const float alpha = __builtin_amdgcn_exp2f(mrow[reg] - mnew);
;         mrow[reg] = mnew;
;         float rsum = 0.f;
; #pragma unroll
;         for (int t8 = 0; t8 < 8; ++t8) {
;           const float p = __builtin_amdgcn_exp2f(sacc[t8][reg] - mnew);
;           rsum += p;
;           sm_p[(wid * 16 + (lane_c >> 4) * 4 + reg) * 136 + t8 * 16 + (lane_c & 15)] = f2bf(p);
;         }
;         rsum = row16_sum(rsum);
;         lrow[reg] = lrow[reg] * alpha + rsum;
; #pragma unroll
;         for (int td = 0; td < 4; ++td) o[td][reg] *= alpha;
;       }
;       asm volatile("s_waitcnt lgkmcnt(0)" ::: "memory");
; #pragma unroll
;       for (int s4 = 0; s4 < 4; ++s4) {
;         const bf16x8 pf = *reinterpret_cast<const bf16x8*>(&sm_p[(wid * 16 + (lane_c & 15)) * 136 + s4 * 32 + (lane_c >> 4) * 8]);
; #pragma unroll
;         for (int td = 0; td < 4; ++td) {
;           const bf16x8 vf = *reinterpret_cast<const bf16x8*>(&sm_vt[(td * 16 + (lane_c & 15)) * 136 + s4 * 32 + (lane_c >> 4) * 8]);
;           o[td] = __builtin_amdgcn_mfma_f32_16x16x32_bf16(pf, vf, o[td], 0, 0, 0);
;         }
;       }
	v_exp_f32_e32 v1, v1
	ds_write_b128 v150, v[80:83] offset:0
	v_exp_f32_e32 v2, v2
	ds_write_b128 v150, v[84:87] offset:4096
	v_exp_f32_e32 v3, v3
	ds_write_b128 v150, v[88:91] offset:8192
	v_exp_f32_e32 v4, v4
	ds_write_b128 v150, v[92:95] offset:12288
	v_exp_f32_e32 v5, v5
	ds_write_b64 v151, v[96:97] offset:0
	v_exp_f32_e32 v6, v6
	ds_write_b64 v229, v[98:99] offset:0
	v_exp_f32_e32 v7, v7
	ds_write_b64 v151, v[100:101] offset:4096
	v_exp_f32_e32 v8, v8
	ds_write_b64 v229, v[102:103] offset:4096
	v_exp_f32_e32 v9, v9
	ds_write_b64 v151, v[104:105] offset:8192
	v_exp_f32_e32 v10, v10
	ds_write_b64 v229, v[106:107] offset:8192
	v_exp_f32_e32 v11, v11
	ds_write_b64 v151, v[108:109] offset:12288
	v_exp_f32_e32 v12, v12
	ds_write_b64 v229, v[110:111] offset:12288
	v_exp_f32_e32 v13, v13
	s_add_u32 s100, s16, 0xc0000
	v_exp_f32_e32 v14, v14
	s_addc_u32 s101, s17, 0
	v_exp_f32_e32 v15, v15
	s_add_u32 s0, s36, 0x100
	v_exp_f32_e32 v16, v16
	s_addc_u32 s1, s37, 0
	v_exp_f32_e32 v17, v17
	global_load_dwordx4 v[80:83], v154, s[100:101] offset:2048
	v_exp_f32_e32 v18, v18
	global_load_dwordx4 v[96:99], v162, s[0:1]
	v_exp_f32_e32 v19, v19
	global_load_dwordx4 v[84:87], v155, s[100:101] offset:2048
	v_exp_f32_e32 v20, v20
	global_load_dwordx4 v[100:103], v163, s[0:1]
	v_exp_f32_e32 v21, v21
	global_load_dwordx4 v[88:91], v156, s[100:101] offset:2048
	v_exp_f32_e32 v22, v22
	global_load_dwordx4 v[104:107], v164, s[0:1]
	v_exp_f32_e32 v23, v23
	global_load_dwordx4 v[92:95], v157, s[100:101] offset:2048
	global_load_dwordx4 v[108:111], v165, s[0:1]
	s_and_b32 s0, s3, 0xff
	s_add_u32 s0, s0, 1
	s_min_u32 s0, s0, 15
	s_lshr_b32 s1, s0, 2
	s_and_b32 s0, s0, 3
	s_lshl_b32 s0, s0, 5
	s_lshr_b32 vcc_lo, s3, 12
	s_add_u32 s0, s0, vcc_lo
	s_sub_i32 vcc_lo, s0, 4
	s_max_i32 vcc_lo, vcc_lo, 0
	s_min_i32 vcc_lo, vcc_lo, 0x78
	s_lshl_b32 vcc_hi, s1, 13
	s_lshl_b32 m0, vcc_lo, 6
	s_add_u32 m0, m0, vcc_hi
	s_mul_i32 m0, m0, 0x1800
	s_add_u32 s12, s4, m0
	s_addc_u32 s13, s5, 0
	s_lshl_b32 m0, s1, 24
	s_lshl_b32 s100, vcc_lo, 7
	s_add_u32 m0, m0, s100
	s_add_u32 s14, s6, m0
	s_addc_u32 s15, s7, 0
	s_lshl_b32 m0, s0, 6
	s_add_u32 m0, m0, vcc_hi
	s_mul_i32 m0, m0, 0x1800
	s_add_u32 s100, s4, m0
	s_addc_u32 s101, s5, 0
	global_load_dwordx4 v[72:75], v166, s[100:101]
	global_load_dwordx4 v[76:79], v166, s[100:101] offset:64
	ds_read_b128 v[112:115], v146 offset:32768
	ds_read_b128 v[116:119], v146 offset:36864
	ds_read_b128 v[120:123], v146 offset:40960
	ds_read_b128 v[124:127], v146 offset:45056
	ds_read_b128 v[128:131], v147 offset:32768
	ds_read_b128 v[132:135], v147 offset:36864
	ds_read_b128 v[136:139], v147 offset:40960
	ds_read_b128 v[140:143], v147 offset:45056
	v_mov_b32_e32 v221, v220
	v_pk_add_f32 v[222:223], v[0:1], v[2:3]
	v_pk_add_f32 v[222:223], v[222:223], v[4:5]
	v_pk_add_f32 v[222:223], v[222:223], v[6:7]
	v_pk_add_f32 v[222:223], v[222:223], v[8:9]
	v_pk_add_f32 v[222:223], v[222:223], v[10:11]
	v_pk_add_f32 v[222:223], v[222:223], v[12:13]
	v_pk_add_f32 v[222:223], v[222:223], v[14:15]
	v_pk_add_f32 v[222:223], v[222:223], v[16:17]
	v_pk_add_f32 v[222:223], v[222:223], v[18:19]
	v_pk_add_f32 v[222:223], v[222:223], v[20:21]
	v_pk_add_f32 v[222:223], v[222:223], v[22:23]
	v_pk_mul_f32 v[32:33], v[32:33], v[220:221]
	v_pk_mul_f32 v[34:35], v[34:35], v[220:221]
	v_pk_mul_f32 v[36:37], v[36:37], v[220:221]
	v_pk_mul_f32 v[38:39], v[38:39], v[220:221]
	v_pk_mul_f32 v[40:41], v[40:41], v[220:221]
	v_pk_mul_f32 v[42:43], v[42:43], v[220:221]
	v_pk_mul_f32 v[44:45], v[44:45], v[220:221]
	v_pk_mul_f32 v[46:47], v[46:47], v[220:221]
	v_add_f32_e32 v203, v222, v223
	v_fma_f32 v201, v201, v220, v203
	v_cvt_pk_bf16_f32 v48, v0, v1
	v_cvt_pk_bf16_f32 v49, v2, v3
	v_cvt_pk_bf16_f32 v50, v4, v5
	v_cvt_pk_bf16_f32 v51, v6, v7
	v_cvt_pk_bf16_f32 v52, v8, v9
	v_cvt_pk_bf16_f32 v53, v10, v11
	v_cvt_pk_bf16_f32 v54, v12, v13
	v_cvt_pk_bf16_f32 v55, v14, v15
	v_cvt_pk_bf16_f32 v56, v16, v17
	v_cvt_pk_bf16_f32 v57, v18, v19
	v_cvt_pk_bf16_f32 v58, v20, v21
	v_cvt_pk_bf16_f32 v59, v22, v23
	s_waitcnt lgkmcnt(7)
	v_mfma_f32_16x16x32_bf16 v[32:35], v[112:115], v[48:51], v[32:35]
	ds_read_b128 v[112:115], v148 offset:32768
	s_waitcnt lgkmcnt(7)
	v_mfma_f32_16x16x32_bf16 v[36:39], v[116:119], v[48:51], v[36:39]
	ds_read_b128 v[116:119], v148 offset:36864
	s_waitcnt lgkmcnt(7)
	v_mfma_f32_16x16x32_bf16 v[40:43], v[120:123], v[48:51], v[40:43]
	ds_read_b128 v[120:123], v148 offset:40960
	s_waitcnt lgkmcnt(7)
	v_mfma_f32_16x16x32_bf16 v[44:47], v[124:127], v[48:51], v[44:47]
	ds_read_b128 v[124:127], v148 offset:45056
	s_waitcnt lgkmcnt(7)
	v_mfma_f32_16x16x32_bf16 v[32:35], v[128:131], v[52:55], v[32:35]
	s_waitcnt lgkmcnt(6)
	v_mfma_f32_16x16x32_bf16 v[36:39], v[132:135], v[52:55], v[36:39]
	s_waitcnt lgkmcnt(5)
	v_mfma_f32_16x16x32_bf16 v[40:43], v[136:139], v[52:55], v[40:43]
	s_waitcnt lgkmcnt(4)
	v_mfma_f32_16x16x32_bf16 v[44:47], v[140:143], v[52:55], v[44:47]
	s_waitcnt lgkmcnt(3)
	v_mfma_f32_16x16x32_bf16 v[32:35], v[112:115], v[56:59], v[32:35]
	s_waitcnt lgkmcnt(2)
	v_mfma_f32_16x16x32_bf16 v[36:39], v[116:119], v[56:59], v[36:39]
	s_waitcnt lgkmcnt(1)
	v_mfma_f32_16x16x32_bf16 v[40:43], v[120:123], v[56:59], v[40:43]
	s_waitcnt lgkmcnt(0)
	v_mfma_f32_16x16x32_bf16 v[44:47], v[124:127], v[56:59], v[44:47]
	s_waitcnt lgkmcnt(0)
	s_barrier
; __device__ __forceinline__ void attn_phase(const Params& P, char* smem_raw) {
;     ...
;       for (int s = 0; s < 2; ++s)
; #pragma unroll
;         for (int t8 = 0; t8 < 8; ++t8) {
;           const bf16x8 kf = *reinterpret_cast<const bf16x8*>(&sm_k[(t8 * 16 + (lane_c & 15)) * LDSS + s * 32 + (lane_c >> 4) * 8]);
;           sacc[t8] = __builtin_amdgcn_mfma_f32_16x16x32_bf16(qf[s], kf, sacc[t8], 0, 0, 0);
;         }
;       if (ck < 5) {
;         ATT_ISSUE(t, ck + 1)
;       } else if (t + VGRID < 8192) {
;         ATT_ISSUE(t + VGRID, 0)
;         ATT_QLOAD(t + VGRID)
;       }
;       if (ck < 4) {
;         const float* rb0 = sm_rpb + (rs + ck * 2 - r + 7) * 31;
; #pragma unroll
;         for (int t8 = 0; t8 < 8; ++t8)
; #pragma unroll
;           for (int reg = 0; reg < 4; ++reg)
;             sacc[t8][reg] += rb0[(t8 >> 2) * 31 + dco[reg][t8 & 3]];
;       }
; #pragma unroll
;       for (int reg = 0; reg < 4; ++reg) {
;         float mx = sacc[0][reg];
; #pragma unroll
;         for (int t8 = 1; t8 < 8; ++t8) mx = fmaxf(mx, sacc[t8][reg]);
;         mx = row16_max(mx);
;         const float mnew = fmaxf(mrow[reg], mx);
;         const float alpha = __builtin_amdgcn_exp2f(mrow[reg] - mnew);
;         mrow[reg] = mnew;
;         float rsum = 0.f;
; #pragma unroll
;         for (int t8 = 0; t8 < 8; ++t8) {
;           const float p = __builtin_amdgcn_exp2f(sacc[t8][reg] - mnew);
;           rsum += p;
;           sm_p[(wid * 16 + (lane_c >> 4) * 4 + reg) * 136 + t8 * 16 + (lane_c & 15)] = f2bf(p);
;         }
;         rsum = row16_sum(rsum);
;         lrow[reg] = lrow[reg] * alpha + rsum;
; #pragma unroll
;         for (int td = 0; td < 4; ++td) o[td][reg] *= alpha;
;       }
	ds_read_b128 v[112:115], v149 offset:0
	ds_read_b128 v[116:119], v224 offset:0
	ds_read_b128 v[120:123], v149 offset:8192
	ds_read_b128 v[124:127], v224 offset:8192
	ds_read_b128 v[128:131], v149 offset:2048
	ds_read_b128 v[132:135], v224 offset:2048
	ds_read_b128 v[136:139], v149 offset:10240
	ds_read_b128 v[140:143], v224 offset:10240
	s_waitcnt lgkmcnt(7)
	v_mfma_f32_16x16x32_bf16 v[0:3], v[112:115], v[64:67], 0
	ds_read_b128 v[112:115], v149 offset:4096
	s_waitcnt lgkmcnt(7)
	v_mfma_f32_16x16x32_bf16 v[0:3], v[116:119], v[68:71], v[0:3]
	ds_read_b128 v[116:119], v224 offset:4096
	s_waitcnt lgkmcnt(7)
	v_mfma_f32_16x16x32_bf16 v[4:7], v[120:123], v[64:67], 0
	ds_read_b128 v[120:123], v149 offset:12288
	s_waitcnt lgkmcnt(7)
	v_mfma_f32_16x16x32_bf16 v[4:7], v[124:127], v[68:71], v[4:7]
	ds_read_b128 v[124:127], v224 offset:12288
	s_waitcnt lgkmcnt(7)
	v_mfma_f32_16x16x32_bf16 v[8:11], v[128:131], v[64:67], 0
	ds_read_b128 v[128:131], v149 offset:6144
	s_waitcnt lgkmcnt(7)
	v_mfma_f32_16x16x32_bf16 v[8:11], v[132:135], v[68:71], v[8:11]
	ds_read_b128 v[132:135], v224 offset:6144
	s_waitcnt lgkmcnt(7)
	v_mfma_f32_16x16x32_bf16 v[12:15], v[136:139], v[64:67], 0
	ds_read_b128 v[136:139], v149 offset:14336
	s_waitcnt lgkmcnt(7)
	v_mfma_f32_16x16x32_bf16 v[12:15], v[140:143], v[68:71], v[12:15]
	ds_read_b128 v[140:143], v224 offset:14336
	s_waitcnt lgkmcnt(7)
	v_mfma_f32_16x16x32_bf16 v[16:19], v[112:115], v[64:67], 0
	s_waitcnt lgkmcnt(6)
	v_mfma_f32_16x16x32_bf16 v[16:19], v[116:119], v[68:71], v[16:19]
	s_waitcnt lgkmcnt(5)
	v_mfma_f32_16x16x32_bf16 v[20:23], v[120:123], v[64:67], 0
	s_waitcnt lgkmcnt(4)
	v_mfma_f32_16x16x32_bf16 v[20:23], v[124:127], v[68:71], v[20:23]
	s_waitcnt lgkmcnt(3)
	v_mfma_f32_16x16x32_bf16 v[24:27], v[128:131], v[64:67], 0
	s_waitcnt lgkmcnt(2)
	v_mfma_f32_16x16x32_bf16 v[24:27], v[132:135], v[68:71], v[24:27]
	s_waitcnt lgkmcnt(1)
	v_mfma_f32_16x16x32_bf16 v[28:31], v[136:139], v[64:67], 0
	s_waitcnt lgkmcnt(0)
	v_mfma_f32_16x16x32_bf16 v[28:31], v[140:143], v[68:71], v[28:31]
	s_nop 7
	v_max3_f32 v203, v0, v1, v2
	v_max3_f32 v203, v203, v3, v4
	v_max3_f32 v203, v203, v5, v6
	v_max3_f32 v203, v203, v7, v8
	v_max3_f32 v203, v203, v9, v10
	v_max3_f32 v203, v203, v11, v12
	v_max3_f32 v203, v203, v13, v14
	v_max3_f32 v203, v203, v15, v16
	v_max3_f32 v203, v203, v17, v18
	v_max3_f32 v203, v203, v19, v20
	v_max3_f32 v203, v203, v21, v22
	v_max3_f32 v203, v203, v23, v24
	v_max3_f32 v203, v203, v25, v26
	v_max3_f32 v203, v203, v27, v28
	v_max3_f32 v203, v203, v29, v30
	v_max_f32_e32 v203, v203, v31
	v_mov_b32_e32 v205, v203
	s_nop 1
	v_permlane16_swap_b32_e32 v203, v205
	v_max_f32_e32 v203, v203, v205
	v_mov_b32_e32 v205, v203
	s_nop 1
	v_permlane32_swap_b32_e32 v203, v205
	v_max_f32_e32 v203, v203, v205
	v_max_f32_e32 v218, v200, v203
	v_sub_f32_e32 v220, v200, v218
	v_mov_b32_e32 v219, v218
	v_exp_f32_e32 v220, v220
	v_mov_b32_e32 v200, v218
	v_pk_add_f32 v[0:1], v[0:1], v[218:219] neg_lo:[0,1] neg_hi:[0,1]
	v_pk_add_f32 v[2:3], v[2:3], v[218:219] neg_lo:[0,1] neg_hi:[0,1]
	v_pk_add_f32 v[4:5], v[4:5], v[218:219] neg_lo:[0,1] neg_hi:[0,1]
	v_pk_add_f32 v[6:7], v[6:7], v[218:219] neg_lo:[0,1] neg_hi:[0,1]
	v_pk_add_f32 v[8:9], v[8:9], v[218:219] neg_lo:[0,1] neg_hi:[0,1]
	v_pk_add_f32 v[10:11], v[10:11], v[218:219] neg_lo:[0,1] neg_hi:[0,1]
	v_pk_add_f32 v[12:13], v[12:13], v[218:219] neg_lo:[0,1] neg_hi:[0,1]
	v_pk_add_f32 v[14:15], v[14:15], v[218:219] neg_lo:[0,1] neg_hi:[0,1]
	v_pk_add_f32 v[16:17], v[16:17], v[218:219] neg_lo:[0,1] neg_hi:[0,1]
	v_pk_add_f32 v[18:19], v[18:19], v[218:219] neg_lo:[0,1] neg_hi:[0,1]
	v_pk_add_f32 v[20:21], v[20:21], v[218:219] neg_lo:[0,1] neg_hi:[0,1]
	v_pk_add_f32 v[22:23], v[22:23], v[218:219] neg_lo:[0,1] neg_hi:[0,1]
	v_pk_add_f32 v[24:25], v[24:25], v[218:219] neg_lo:[0,1] neg_hi:[0,1]
	v_pk_add_f32 v[26:27], v[26:27], v[218:219] neg_lo:[0,1] neg_hi:[0,1]
	v_pk_add_f32 v[28:29], v[28:29], v[218:219] neg_lo:[0,1] neg_hi:[0,1]
	v_pk_add_f32 v[30:31], v[30:31], v[218:219] neg_lo:[0,1] neg_hi:[0,1]
	v_exp_f32_e32 v0, v0
	s_waitcnt vmcnt(2)
	v_exp_f32_e32 v1, v1
	ds_write_b128 v150, v[80:83] offset:32768
	v_exp_f32_e32 v2, v2
	ds_write_b128 v150, v[84:87] offset:36864
	v_exp_f32_e32 v3, v3
	ds_write_b128 v150, v[88:91] offset:40960
	v_exp_f32_e32 v4, v4
	ds_write_b128 v150, v[92:95] offset:45056
	v_exp_f32_e32 v5, v5
	ds_write_b64 v151, v[96:97] offset:32768
	v_exp_f32_e32 v6, v6
	ds_write_b64 v229, v[98:99] offset:32768
	v_exp_f32_e32 v7, v7
	ds_write_b64 v151, v[100:101] offset:36864
	v_exp_f32_e32 v8, v8
	ds_write_b64 v229, v[102:103] offset:36864
	v_exp_f32_e32 v9, v9
	ds_write_b64 v151, v[104:105] offset:40960
	v_exp_f32_e32 v10, v10
	ds_write_b64 v229, v[106:107] offset:40960
	v_exp_f32_e32 v11, v11
	ds_write_b64 v151, v[108:109] offset:45056
	v_exp_f32_e32 v12, v12
	ds_write_b64 v229, v[110:111] offset:45056
	v_exp_f32_e32 v13, v13
	s_add_u32 s100, s12, 0x0
	v_exp_f32_e32 v14, v14
	s_addc_u32 s101, s13, 0
	v_exp_f32_e32 v15, v15
	s_add_u32 s0, s14, 0x0
	v_exp_f32_e32 v16, v16
	s_addc_u32 s1, s15, 0
	v_exp_f32_e32 v17, v17
	global_load_dwordx4 v[80:83], v154, s[100:101] offset:2048
	v_exp_f32_e32 v18, v18
	global_load_dwordx4 v[96:99], v158, s[0:1]
	v_exp_f32_e32 v19, v19
	global_load_dwordx4 v[84:87], v155, s[100:101] offset:2048
	v_exp_f32_e32 v20, v20
	global_load_dwordx4 v[100:103], v159, s[0:1]
	v_exp_f32_e32 v21, v21
	global_load_dwordx4 v[88:91], v156, s[100:101] offset:2048
	v_exp_f32_e32 v22, v22
	global_load_dwordx4 v[104:107], v160, s[0:1]
	v_exp_f32_e32 v23, v23
	global_load_dwordx4 v[92:95], v157, s[100:101] offset:2048
	v_exp_f32_e32 v24, v24
; __device__ __forceinline__ void attn_phase(const Params& P, char* smem_raw) {
;     ...
;       if (ck < 4) {
;         const float* rb0 = sm_rpb + (rs + ck * 2 - r + 7) * 31;
; #pragma unroll
;         for (int t8 = 0; t8 < 8; ++t8)
; #pragma unroll
;           for (int reg = 0; reg < 4; ++reg)
;             sacc[t8][reg] += rb0[(t8 >> 2) * 31 + dco[reg][t8 & 3]];
;       }
; #pragma unroll
;       for (int reg = 0; reg < 4; ++reg) {
;         float mx = sacc[0][reg];
; #pragma unroll
;         for (int t8 = 1; t8 < 8; ++t8) mx = fmaxf(mx, sacc[t8][reg]);
;         mx = row16_max(mx);
;         const float mnew = fmaxf(mrow[reg], mx);
;         const float alpha = __builtin_amdgcn_exp2f(mrow[reg] - mnew);
;         mrow[reg] = mnew;
;         float rsum = 0.f;
; #pragma unroll
;         for (int t8 = 0; t8 < 8; ++t8) {
;           const float p = __builtin_amdgcn_exp2f(sacc[t8][reg] - mnew);
;           rsum += p;
;           sm_p[(wid * 16 + (lane_c >> 4) * 4 + reg) * 136 + t8 * 16 + (lane_c & 15)] = f2bf(p);
;         }
;         rsum = row16_sum(rsum);
;         lrow[reg] = lrow[reg] * alpha + rsum;
; #pragma unroll
;         for (int td = 0; td < 4; ++td) o[td][reg] *= alpha;
;       }
;       asm volatile("s_waitcnt lgkmcnt(0)" ::: "memory");
; #pragma unroll
;       for (int s4 = 0; s4 < 4; ++s4) {
;         const bf16x8 pf = *reinterpret_cast<const bf16x8*>(&sm_p[(wid * 16 + (lane_c & 15)) * 136 + s4 * 32 + (lane_c >> 4) * 8]);
; #pragma unroll
;         for (int td = 0; td < 4; ++td) {
;           const bf16x8 vf = *reinterpret_cast<const bf16x8*>(&sm_vt[(td * 16 + (lane_c & 15)) * 136 + s4 * 32 + (lane_c >> 4) * 8]);
;           o[td] = __builtin_amdgcn_mfma_f32_16x16x32_bf16(pf, vf, o[td], 0, 0, 0);
;         }
;       }
	global_load_dwordx4 v[108:111], v161, s[0:1]
	v_exp_f32_e32 v25, v25
	v_exp_f32_e32 v26, v26
	v_exp_f32_e32 v27, v27
	v_exp_f32_e32 v28, v28
	v_exp_f32_e32 v29, v29
	v_exp_f32_e32 v30, v30
	v_exp_f32_e32 v31, v31
	s_and_b32 s0, s3, 0xff
	s_add_u32 s0, s0, 1
	s_min_u32 s0, s0, 15
	s_lshr_b32 s1, s0, 2
	s_and_b32 s0, s0, 3
	s_lshl_b32 s0, s0, 5
	s_lshr_b32 vcc_lo, s3, 12
	s_add_u32 s0, s0, vcc_lo
	s_sub_i32 vcc_lo, s0, 4
	s_max_i32 vcc_lo, vcc_lo, 0
	s_min_i32 vcc_lo, vcc_lo, 0x78
	s_lshl_b32 vcc_hi, s1, 13
	s_sub_i32 vcc_lo, vcc_lo, s0
	s_add_i32 vcc_lo, vcc_lo, 4
	s_lshl_b32 vcc_lo, vcc_lo, 7
	s_bfe_u32 m0, s3, 0x10008
	s_mul_i32 m0, m0, 0x12000
	s_add_i32 vcc_lo, vcc_lo, m0
	s_add_i32 vcc_lo, vcc_lo, 0x10010
	v_add_u32_e32 v184, vcc_lo, v168
	v_add_u32_e32 v185, vcc_lo, v169
	v_add_u32_e32 v186, vcc_lo, v170
	v_add_u32_e32 v187, vcc_lo, v171
	v_add_u32_e32 v188, vcc_lo, v172
	v_add_u32_e32 v189, vcc_lo, v173
	v_add_u32_e32 v190, vcc_lo, v174
	v_add_u32_e32 v191, vcc_lo, v175
	v_add_u32_e32 v192, vcc_lo, v176
	v_add_u32_e32 v193, vcc_lo, v177
	v_add_u32_e32 v194, vcc_lo, v178
	v_add_u32_e32 v195, vcc_lo, v179
	ds_read_b128 v[112:115], v225 offset:0
	ds_read_b128 v[116:119], v225 offset:4096
	ds_read_b128 v[120:123], v225 offset:8192
	ds_read_b128 v[124:127], v225 offset:12288
	ds_read_b128 v[128:131], v226 offset:0
	ds_read_b128 v[132:135], v226 offset:4096
	ds_read_b128 v[136:139], v226 offset:8192
	ds_read_b128 v[140:143], v226 offset:12288
	v_mov_b32_e32 v221, v220
	v_pk_add_f32 v[222:223], v[0:1], v[2:3]
	v_pk_add_f32 v[222:223], v[222:223], v[4:5]
	v_pk_add_f32 v[222:223], v[222:223], v[6:7]
	v_pk_add_f32 v[222:223], v[222:223], v[8:9]
	v_pk_add_f32 v[222:223], v[222:223], v[10:11]
	v_pk_add_f32 v[222:223], v[222:223], v[12:13]
	v_pk_add_f32 v[222:223], v[222:223], v[14:15]
	v_pk_add_f32 v[222:223], v[222:223], v[16:17]
	v_pk_add_f32 v[222:223], v[222:223], v[18:19]
	v_pk_add_f32 v[222:223], v[222:223], v[20:21]
	v_pk_add_f32 v[222:223], v[222:223], v[22:23]
	v_pk_add_f32 v[222:223], v[222:223], v[24:25]
	v_pk_add_f32 v[222:223], v[222:223], v[26:27]
	v_pk_add_f32 v[222:223], v[222:223], v[28:29]
	v_pk_add_f32 v[222:223], v[222:223], v[30:31]
	v_pk_mul_f32 v[32:33], v[32:33], v[220:221]
	v_pk_mul_f32 v[34:35], v[34:35], v[220:221]
	v_pk_mul_f32 v[36:37], v[36:37], v[220:221]
	v_pk_mul_f32 v[38:39], v[38:39], v[220:221]
	v_pk_mul_f32 v[40:41], v[40:41], v[220:221]
	v_pk_mul_f32 v[42:43], v[42:43], v[220:221]
	v_pk_mul_f32 v[44:45], v[44:45], v[220:221]
	v_pk_mul_f32 v[46:47], v[46:47], v[220:221]
	v_add_f32_e32 v203, v222, v223
	v_fma_f32 v201, v201, v220, v203
	v_cvt_pk_bf16_f32 v48, v0, v1
	v_cvt_pk_bf16_f32 v49, v2, v3
	v_cvt_pk_bf16_f32 v50, v4, v5
	v_cvt_pk_bf16_f32 v51, v6, v7
	v_cvt_pk_bf16_f32 v52, v8, v9
	v_cvt_pk_bf16_f32 v53, v10, v11
	v_cvt_pk_bf16_f32 v54, v12, v13
	v_cvt_pk_bf16_f32 v55, v14, v15
	v_cvt_pk_bf16_f32 v56, v16, v17
	v_cvt_pk_bf16_f32 v57, v18, v19
	v_cvt_pk_bf16_f32 v58, v20, v21
	v_cvt_pk_bf16_f32 v59, v22, v23
	v_cvt_pk_bf16_f32 v60, v24, v25
	v_cvt_pk_bf16_f32 v61, v26, v27
	v_cvt_pk_bf16_f32 v62, v28, v29
	v_cvt_pk_bf16_f32 v63, v30, v31
	s_waitcnt lgkmcnt(7)
	v_mfma_f32_16x16x32_bf16 v[32:35], v[112:115], v[48:51], v[32:35]
	ds_read_b128 v[112:115], v227 offset:0
	s_waitcnt lgkmcnt(7)
	v_mfma_f32_16x16x32_bf16 v[36:39], v[116:119], v[48:51], v[36:39]
	ds_read_b128 v[116:119], v227 offset:4096
	s_waitcnt lgkmcnt(7)
	v_mfma_f32_16x16x32_bf16 v[40:43], v[120:123], v[48:51], v[40:43]
	ds_read_b128 v[120:123], v227 offset:8192
	s_waitcnt lgkmcnt(7)
	v_mfma_f32_16x16x32_bf16 v[44:47], v[124:127], v[48:51], v[44:47]
	ds_read_b128 v[124:127], v227 offset:12288
	s_waitcnt lgkmcnt(7)
	v_mfma_f32_16x16x32_bf16 v[32:35], v[128:131], v[52:55], v[32:35]
	ds_read_b128 v[128:131], v228 offset:0
	s_waitcnt lgkmcnt(7)
	v_mfma_f32_16x16x32_bf16 v[36:39], v[132:135], v[52:55], v[36:39]
	ds_read_b128 v[132:135], v228 offset:4096
	s_waitcnt lgkmcnt(7)
	v_mfma_f32_16x16x32_bf16 v[40:43], v[136:139], v[52:55], v[40:43]
	ds_read_b128 v[136:139], v228 offset:8192
	s_waitcnt lgkmcnt(7)
	v_mfma_f32_16x16x32_bf16 v[44:47], v[140:143], v[52:55], v[44:47]
	ds_read_b128 v[140:143], v228 offset:12288
	s_waitcnt lgkmcnt(7)
	v_mfma_f32_16x16x32_bf16 v[32:35], v[112:115], v[56:59], v[32:35]
	s_waitcnt lgkmcnt(6)
	v_mfma_f32_16x16x32_bf16 v[36:39], v[116:119], v[56:59], v[36:39]
	s_waitcnt lgkmcnt(5)
	v_mfma_f32_16x16x32_bf16 v[40:43], v[120:123], v[56:59], v[40:43]
	s_waitcnt lgkmcnt(4)
	v_mfma_f32_16x16x32_bf16 v[44:47], v[124:127], v[56:59], v[44:47]
	s_waitcnt lgkmcnt(3)
	v_mfma_f32_16x16x32_bf16 v[32:35], v[128:131], v[60:63], v[32:35]
	s_waitcnt lgkmcnt(2)
	v_mfma_f32_16x16x32_bf16 v[36:39], v[132:135], v[60:63], v[36:39]
	s_waitcnt lgkmcnt(1)
	v_mfma_f32_16x16x32_bf16 v[40:43], v[136:139], v[60:63], v[40:43]
	s_waitcnt lgkmcnt(0)
	v_mfma_f32_16x16x32_bf16 v[44:47], v[140:143], v[60:63], v[44:47]
	s_waitcnt lgkmcnt(0)
	s_barrier
; __device__ __forceinline__ void attn_phase(const Params& P, char* smem_raw) {
;     ...
;       for (int s = 0; s < 2; ++s)
; #pragma unroll
;         for (int t8 = 0; t8 < 8; ++t8) {
;           const bf16x8 kf = *reinterpret_cast<const bf16x8*>(&sm_k[(t8 * 16 + (lane_c & 15)) * LDSS + s * 32 + (lane_c >> 4) * 8]);
;           sacc[t8] = __builtin_amdgcn_mfma_f32_16x16x32_bf16(qf[s], kf, sacc[t8], 0, 0, 0);
;         }
;       if (ck < 5) {
;         ATT_ISSUE(t, ck + 1)
;       } else if (t + VGRID < 8192) {
;         ATT_ISSUE(t + VGRID, 0)
;         ATT_QLOAD(t + VGRID)
;       }
;       if (ck < 4) {
;         const float* rb0 = sm_rpb + (rs + ck * 2 - r + 7) * 31;
; #pragma unroll
;         for (int t8 = 0; t8 < 8; ++t8)
; #pragma unroll
;           for (int reg = 0; reg < 4; ++reg)
;             sacc[t8][reg] += rb0[(t8 >> 2) * 31 + dco[reg][t8 & 3]];
;       }
; #pragma unroll
;       for (int reg = 0; reg < 4; ++reg) {
;         float mx = sacc[0][reg];
; #pragma unroll
;         for (int t8 = 1; t8 < 8; ++t8) mx = fmaxf(mx, sacc[t8][reg]);
;         mx = row16_max(mx);
;         const float mnew = fmaxf(mrow[reg], mx);
;         const float alpha = __builtin_amdgcn_exp2f(mrow[reg] - mnew);
;         mrow[reg] = mnew;
;         float rsum = 0.f;
; #pragma unroll
;         for (int t8 = 0; t8 < 8; ++t8) {
;           const float p = __builtin_amdgcn_exp2f(sacc[t8][reg] - mnew);
;           rsum += p;
;           sm_p[(wid * 16 + (lane_c >> 4) * 4 + reg) * 136 + t8 * 16 + (lane_c & 15)] = f2bf(p);
;         }
;         rsum = row16_sum(rsum);
;         lrow[reg] = lrow[reg] * alpha + rsum;
; #pragma unroll
;         for (int td = 0; td < 4; ++td) o[td][reg] *= alpha;
;       }
	ds_read_b128 v[112:115], v149 offset:32768
	ds_read_b128 v[116:119], v224 offset:32768
	ds_read_b128 v[120:123], v149 offset:40960
	ds_read_b128 v[124:127], v224 offset:40960
	ds_read_b128 v[128:131], v149 offset:34816
	ds_read_b128 v[132:135], v224 offset:34816
	ds_read_b128 v[136:139], v149 offset:43008
	ds_read_b128 v[140:143], v224 offset:43008
	s_waitcnt lgkmcnt(7)
	v_mfma_f32_16x16x32_bf16 v[0:3], v[112:115], v[64:67], 0
	ds_read_b128 v[112:115], v149 offset:36864
	s_waitcnt lgkmcnt(7)
	v_mfma_f32_16x16x32_bf16 v[0:3], v[116:119], v[68:71], v[0:3]
	ds_read_b128 v[116:119], v224 offset:36864
	s_waitcnt lgkmcnt(7)
	v_mfma_f32_16x16x32_bf16 v[4:7], v[120:123], v[64:67], 0
	ds_read_b128 v[120:123], v149 offset:45056
	s_waitcnt lgkmcnt(7)
	v_mfma_f32_16x16x32_bf16 v[4:7], v[124:127], v[68:71], v[4:7]
	ds_read_b128 v[124:127], v224 offset:45056
	s_waitcnt lgkmcnt(7)
	v_mfma_f32_16x16x32_bf16 v[8:11], v[128:131], v[64:67], 0
	ds_read_b128 v[128:131], v149 offset:38912
	s_waitcnt lgkmcnt(7)
	v_mfma_f32_16x16x32_bf16 v[8:11], v[132:135], v[68:71], v[8:11]
	ds_read_b128 v[132:135], v224 offset:38912
	s_waitcnt lgkmcnt(7)
	v_mfma_f32_16x16x32_bf16 v[12:15], v[136:139], v[64:67], 0
	ds_read_b128 v[136:139], v149 offset:47104
	s_waitcnt lgkmcnt(7)
	v_mfma_f32_16x16x32_bf16 v[12:15], v[140:143], v[68:71], v[12:15]
	ds_read_b128 v[140:143], v224 offset:47104
	s_waitcnt lgkmcnt(7)
	v_mfma_f32_16x16x32_bf16 v[16:19], v[112:115], v[64:67], 0
	s_waitcnt lgkmcnt(6)
	v_mfma_f32_16x16x32_bf16 v[16:19], v[116:119], v[68:71], v[16:19]
	s_waitcnt lgkmcnt(5)
	v_mfma_f32_16x16x32_bf16 v[20:23], v[120:123], v[64:67], 0
	s_waitcnt lgkmcnt(4)
	v_mfma_f32_16x16x32_bf16 v[20:23], v[124:127], v[68:71], v[20:23]
	s_waitcnt lgkmcnt(3)
	v_mfma_f32_16x16x32_bf16 v[24:27], v[128:131], v[64:67], 0
	s_waitcnt lgkmcnt(2)
	v_mfma_f32_16x16x32_bf16 v[24:27], v[132:135], v[68:71], v[24:27]
	s_waitcnt lgkmcnt(1)
	v_mfma_f32_16x16x32_bf16 v[28:31], v[136:139], v[64:67], 0
	s_waitcnt lgkmcnt(0)
	v_mfma_f32_16x16x32_bf16 v[28:31], v[140:143], v[68:71], v[28:31]
	s_nop 7
	v_max3_f32 v203, v0, v1, v2
	v_max3_f32 v203, v203, v3, v4
	v_max3_f32 v203, v203, v5, v6
	v_max3_f32 v203, v203, v7, v8
	v_max3_f32 v203, v203, v9, v10
	v_max3_f32 v203, v203, v11, v12
	v_max3_f32 v203, v203, v13, v14
	v_max3_f32 v203, v203, v15, v16
	v_max3_f32 v203, v203, v17, v18
	v_max3_f32 v203, v203, v19, v20
	v_max3_f32 v203, v203, v21, v22
	v_max3_f32 v203, v203, v23, v24
	v_max3_f32 v203, v203, v25, v26
	v_max3_f32 v203, v203, v27, v28
	v_max3_f32 v203, v203, v29, v30
	v_max_f32_e32 v203, v203, v31
	v_mov_b32_e32 v205, v203
	s_nop 1
	v_permlane16_swap_b32_e32 v203, v205
	v_max_f32_e32 v203, v203, v205
	v_mov_b32_e32 v205, v203
	s_nop 1
	v_permlane32_swap_b32_e32 v203, v205
	v_max_f32_e32 v203, v203, v205
	v_max_f32_e32 v218, v200, v203
	v_sub_f32_e32 v220, v200, v218
	v_mov_b32_e32 v219, v218
	v_exp_f32_e32 v220, v220
	v_mov_b32_e32 v200, v218
	v_pk_add_f32 v[0:1], v[0:1], v[218:219] neg_lo:[0,1] neg_hi:[0,1]
	v_pk_add_f32 v[2:3], v[2:3], v[218:219] neg_lo:[0,1] neg_hi:[0,1]
	v_pk_add_f32 v[4:5], v[4:5], v[218:219] neg_lo:[0,1] neg_hi:[0,1]
	v_pk_add_f32 v[6:7], v[6:7], v[218:219] neg_lo:[0,1] neg_hi:[0,1]
	v_pk_add_f32 v[8:9], v[8:9], v[218:219] neg_lo:[0,1] neg_hi:[0,1]
	v_pk_add_f32 v[10:11], v[10:11], v[218:219] neg_lo:[0,1] neg_hi:[0,1]
	v_pk_add_f32 v[12:13], v[12:13], v[218:219] neg_lo:[0,1] neg_hi:[0,1]
	v_pk_add_f32 v[14:15], v[14:15], v[218:219] neg_lo:[0,1] neg_hi:[0,1]
	v_pk_add_f32 v[16:17], v[16:17], v[218:219] neg_lo:[0,1] neg_hi:[0,1]
	v_pk_add_f32 v[18:19], v[18:19], v[218:219] neg_lo:[0,1] neg_hi:[0,1]
	v_pk_add_f32 v[20:21], v[20:21], v[218:219] neg_lo:[0,1] neg_hi:[0,1]
	v_pk_add_f32 v[22:23], v[22:23], v[218:219] neg_lo:[0,1] neg_hi:[0,1]
	v_pk_add_f32 v[24:25], v[24:25], v[218:219] neg_lo:[0,1] neg_hi:[0,1]
	v_pk_add_f32 v[26:27], v[26:27], v[218:219] neg_lo:[0,1] neg_hi:[0,1]
	v_pk_add_f32 v[28:29], v[28:29], v[218:219] neg_lo:[0,1] neg_hi:[0,1]
	v_pk_add_f32 v[30:31], v[30:31], v[218:219] neg_lo:[0,1] neg_hi:[0,1]
	v_exp_f32_e32 v0, v0
	s_waitcnt vmcnt(0)
	v_exp_f32_e32 v1, v1
	ds_write_b128 v150, v[80:83] offset:0
	v_exp_f32_e32 v2, v2
	ds_write_b128 v150, v[84:87] offset:4096
	v_exp_f32_e32 v3, v3
	ds_write_b128 v150, v[88:91] offset:8192
	v_exp_f32_e32 v4, v4
	ds_write_b128 v150, v[92:95] offset:12288
	v_exp_f32_e32 v5, v5
	ds_write_b64 v151, v[96:97] offset:0
	v_exp_f32_e32 v6, v6
	ds_write_b64 v229, v[98:99] offset:0
	v_exp_f32_e32 v7, v7
	ds_write_b64 v151, v[100:101] offset:4096
	v_exp_f32_e32 v8, v8
	ds_write_b64 v229, v[102:103] offset:4096
	v_exp_f32_e32 v9, v9
	ds_write_b64 v151, v[104:105] offset:8192
	v_exp_f32_e32 v10, v10
	ds_write_b64 v229, v[106:107] offset:8192
	v_exp_f32_e32 v11, v11
	ds_write_b64 v151, v[108:109] offset:12288
	v_exp_f32_e32 v12, v12
	ds_write_b64 v229, v[110:111] offset:12288
	v_exp_f32_e32 v13, v13
	s_add_u32 s100, s12, 0xc0000
	v_exp_f32_e32 v14, v14
	s_addc_u32 s101, s13, 0
	v_exp_f32_e32 v15, v15
	s_add_u32 s0, s14, 0x100
	v_exp_f32_e32 v16, v16
	s_addc_u32 s1, s15, 0
	v_exp_f32_e32 v17, v17
	global_load_dwordx4 v[80:83], v154, s[100:101] offset:2048
	v_exp_f32_e32 v18, v18
	global_load_dwordx4 v[96:99], v158, s[0:1]
	v_exp_f32_e32 v19, v19
	global_load_dwordx4 v[84:87], v155, s[100:101] offset:2048
	v_exp_f32_e32 v20, v20
	global_load_dwordx4 v[100:103], v159, s[0:1]
	v_exp_f32_e32 v21, v21
	global_load_dwordx4 v[88:91], v156, s[100:101] offset:2048
	v_exp_f32_e32 v22, v22
	global_load_dwordx4 v[104:107], v160, s[0:1]
	v_exp_f32_e32 v23, v23
	global_load_dwordx4 v[92:95], v157, s[100:101] offset:2048
	v_exp_f32_e32 v24, v24
; __device__ __forceinline__ void attn_phase(const Params& P, char* smem_raw) {
;     ...
; #pragma unroll
;       for (int reg = 0; reg < 4; ++reg) {
;         float mx = sacc[0][reg];
; #pragma unroll
;         for (int t8 = 1; t8 < 8; ++t8) mx = fmaxf(mx, sacc[t8][reg]);
;         mx = row16_max(mx);
;         const float mnew = fmaxf(mrow[reg], mx);
;         const float alpha = __builtin_amdgcn_exp2f(mrow[reg] - mnew);
;         mrow[reg] = mnew;
;         float rsum = 0.f;
; #pragma unroll
;         for (int t8 = 0; t8 < 8; ++t8) {
;           const float p = __builtin_amdgcn_exp2f(sacc[t8][reg] - mnew);
;           rsum += p;
;           sm_p[(wid * 16 + (lane_c >> 4) * 4 + reg) * 136 + t8 * 16 + (lane_c & 15)] = f2bf(p);
;         }
;         rsum = row16_sum(rsum);
;         lrow[reg] = lrow[reg] * alpha + rsum;
; #pragma unroll
;         for (int td = 0; td < 4; ++td) o[td][reg] *= alpha;
;       }
;       asm volatile("s_waitcnt lgkmcnt(0)" ::: "memory");
; #pragma unroll
;       for (int s4 = 0; s4 < 4; ++s4) {
;         const bf16x8 pf = *reinterpret_cast<const bf16x8*>(&sm_p[(wid * 16 + (lane_c & 15)) * 136 + s4 * 32 + (lane_c >> 4) * 8]);
; #pragma unroll
;         for (int td = 0; td < 4; ++td) {
;           const bf16x8 vf = *reinterpret_cast<const bf16x8*>(&sm_vt[(td * 16 + (lane_c & 15)) * 136 + s4 * 32 + (lane_c >> 4) * 8]);
;           o[td] = __builtin_amdgcn_mfma_f32_16x16x32_bf16(pf, vf, o[td], 0, 0, 0);
;         }
;       }
;     }
;     u16* Ob = P.cat + ((long)b * 8192 + r * 64) * 1024 + h * 64;
; #pragma unroll
;     for (int td = 0; td < 4; ++td)
; #pragma unroll
;       for (int reg = 0; reg < 4; ++reg) {
;         const int rowl = wid * 16 + (lane >> 4) * 4 + reg;
;         Ob[(unsigned)(rowl * 1024 + td * 16 + (lane & 15))] = f2bf(o[td][reg] * __builtin_amdgcn_rcpf(lrow[reg]));
;       }
	global_load_dwordx4 v[108:111], v161, s[0:1]
	v_exp_f32_e32 v25, v25
	v_exp_f32_e32 v26, v26
	v_exp_f32_e32 v27, v27
	v_exp_f32_e32 v28, v28
	v_exp_f32_e32 v29, v29
	v_exp_f32_e32 v30, v30
	v_exp_f32_e32 v31, v31
	ds_read_b128 v[112:115], v225 offset:32768
	ds_read_b128 v[116:119], v225 offset:36864
	ds_read_b128 v[120:123], v225 offset:40960
	ds_read_b128 v[124:127], v225 offset:45056
	ds_read_b128 v[128:131], v226 offset:32768
	ds_read_b128 v[132:135], v226 offset:36864
	ds_read_b128 v[136:139], v226 offset:40960
	ds_read_b128 v[140:143], v226 offset:45056
	v_mov_b32_e32 v221, v220
	v_pk_add_f32 v[222:223], v[0:1], v[2:3]
	v_pk_add_f32 v[222:223], v[222:223], v[4:5]
	v_pk_add_f32 v[222:223], v[222:223], v[6:7]
	v_pk_add_f32 v[222:223], v[222:223], v[8:9]
	v_pk_add_f32 v[222:223], v[222:223], v[10:11]
	v_pk_add_f32 v[222:223], v[222:223], v[12:13]
	v_pk_add_f32 v[222:223], v[222:223], v[14:15]
	v_pk_add_f32 v[222:223], v[222:223], v[16:17]
	v_pk_add_f32 v[222:223], v[222:223], v[18:19]
	v_pk_add_f32 v[222:223], v[222:223], v[20:21]
	v_pk_add_f32 v[222:223], v[222:223], v[22:23]
	v_pk_add_f32 v[222:223], v[222:223], v[24:25]
	v_pk_add_f32 v[222:223], v[222:223], v[26:27]
	v_pk_add_f32 v[222:223], v[222:223], v[28:29]
	v_pk_add_f32 v[222:223], v[222:223], v[30:31]
	v_pk_mul_f32 v[32:33], v[32:33], v[220:221]
	v_pk_mul_f32 v[34:35], v[34:35], v[220:221]
	v_pk_mul_f32 v[36:37], v[36:37], v[220:221]
	v_pk_mul_f32 v[38:39], v[38:39], v[220:221]
	v_pk_mul_f32 v[40:41], v[40:41], v[220:221]
	v_pk_mul_f32 v[42:43], v[42:43], v[220:221]
	v_pk_mul_f32 v[44:45], v[44:45], v[220:221]
	v_pk_mul_f32 v[46:47], v[46:47], v[220:221]
	v_add_f32_e32 v203, v222, v223
	v_fma_f32 v201, v201, v220, v203
	v_cvt_pk_bf16_f32 v48, v0, v1
	v_cvt_pk_bf16_f32 v49, v2, v3
	v_cvt_pk_bf16_f32 v50, v4, v5
	v_cvt_pk_bf16_f32 v51, v6, v7
	v_cvt_pk_bf16_f32 v52, v8, v9
	v_cvt_pk_bf16_f32 v53, v10, v11
	v_cvt_pk_bf16_f32 v54, v12, v13
	v_cvt_pk_bf16_f32 v55, v14, v15
	v_cvt_pk_bf16_f32 v56, v16, v17
	v_cvt_pk_bf16_f32 v57, v18, v19
	v_cvt_pk_bf16_f32 v58, v20, v21
	v_cvt_pk_bf16_f32 v59, v22, v23
	v_cvt_pk_bf16_f32 v60, v24, v25
	v_cvt_pk_bf16_f32 v61, v26, v27
	v_cvt_pk_bf16_f32 v62, v28, v29
	v_cvt_pk_bf16_f32 v63, v30, v31
	s_waitcnt lgkmcnt(7)
	v_mfma_f32_16x16x32_bf16 v[32:35], v[112:115], v[48:51], v[32:35]
	ds_read_b128 v[112:115], v227 offset:32768
	s_waitcnt lgkmcnt(7)
	v_mfma_f32_16x16x32_bf16 v[36:39], v[116:119], v[48:51], v[36:39]
	ds_read_b128 v[116:119], v227 offset:36864
	s_waitcnt lgkmcnt(7)
	v_mfma_f32_16x16x32_bf16 v[40:43], v[120:123], v[48:51], v[40:43]
	ds_read_b128 v[120:123], v227 offset:40960
	s_waitcnt lgkmcnt(7)
	v_mfma_f32_16x16x32_bf16 v[44:47], v[124:127], v[48:51], v[44:47]
	ds_read_b128 v[124:127], v227 offset:45056
	s_waitcnt lgkmcnt(7)
	v_mfma_f32_16x16x32_bf16 v[32:35], v[128:131], v[52:55], v[32:35]
	ds_read_b128 v[128:131], v228 offset:32768
	s_waitcnt lgkmcnt(7)
	v_mfma_f32_16x16x32_bf16 v[36:39], v[132:135], v[52:55], v[36:39]
	ds_read_b128 v[132:135], v228 offset:36864
	s_waitcnt lgkmcnt(7)
	v_mfma_f32_16x16x32_bf16 v[40:43], v[136:139], v[52:55], v[40:43]
	ds_read_b128 v[136:139], v228 offset:40960
	s_waitcnt lgkmcnt(7)
	v_mfma_f32_16x16x32_bf16 v[44:47], v[140:143], v[52:55], v[44:47]
	ds_read_b128 v[140:143], v228 offset:45056
	s_waitcnt lgkmcnt(7)
	v_mfma_f32_16x16x32_bf16 v[32:35], v[112:115], v[56:59], v[32:35]
	s_waitcnt lgkmcnt(6)
	v_mfma_f32_16x16x32_bf16 v[36:39], v[116:119], v[56:59], v[36:39]
	s_waitcnt lgkmcnt(5)
	v_mfma_f32_16x16x32_bf16 v[40:43], v[120:123], v[56:59], v[40:43]
	s_waitcnt lgkmcnt(4)
	v_mfma_f32_16x16x32_bf16 v[44:47], v[124:127], v[56:59], v[44:47]
	s_waitcnt lgkmcnt(3)
	v_mfma_f32_16x16x32_bf16 v[32:35], v[128:131], v[60:63], v[32:35]
	s_waitcnt lgkmcnt(2)
	v_mfma_f32_16x16x32_bf16 v[36:39], v[132:135], v[60:63], v[36:39]
	s_waitcnt lgkmcnt(1)
	v_mfma_f32_16x16x32_bf16 v[40:43], v[136:139], v[60:63], v[40:43]
	s_waitcnt lgkmcnt(0)
	v_mfma_f32_16x16x32_bf16 v[44:47], v[140:143], v[60:63], v[44:47]
	ds_read_b32 v0, v184 offset:384
	ds_read_b32 v1, v185 offset:384
	ds_read_b32 v2, v186 offset:384
	ds_read_b32 v3, v187 offset:384
	ds_read_b32 v4, v184 offset:512
	ds_read_b32 v5, v185 offset:512
	ds_read_b32 v6, v186 offset:512
	ds_read_b32 v7, v187 offset:512
	ds_read_b32 v8, v188 offset:384
	ds_read_b32 v9, v189 offset:384
	ds_read_b32 v10, v190 offset:384
	ds_read_b32 v11, v191 offset:384
	ds_read_b32 v12, v188 offset:512
	ds_read_b32 v13, v189 offset:512
	ds_read_b32 v14, v190 offset:512
	ds_read_b32 v15, v191 offset:512
	ds_read_b32 v16, v192 offset:384
	ds_read_b32 v17, v193 offset:384
	ds_read_b32 v18, v194 offset:384
	ds_read_b32 v19, v195 offset:384
	ds_read_b32 v20, v192 offset:512
	ds_read_b32 v21, v193 offset:512
	ds_read_b32 v22, v194 offset:512
	ds_read_b32 v23, v195 offset:512
	s_waitcnt lgkmcnt(0)
	v_mov_b32_e32 v205, v201
	s_nop 1
	v_permlane16_swap_b32_e32 v201, v205
	v_add_f32_e32 v201, v201, v205
	v_mov_b32_e32 v205, v201
	s_nop 1
	v_permlane32_swap_b32_e32 v201, v205
	v_add_f32_e32 v201, v201, v205
	v_rcp_f32_e32 v203, v201
	s_nop 7
	v_mul_f32_e32 v32, v32, v203
	v_mul_f32_e32 v33, v33, v203
	v_mul_f32_e32 v34, v34, v203
	v_mul_f32_e32 v35, v35, v203
	v_mul_f32_e32 v36, v36, v203
	v_mul_f32_e32 v37, v37, v203
	v_mul_f32_e32 v38, v38, v203
	v_mul_f32_e32 v39, v39, v203
	v_mul_f32_e32 v40, v40, v203
	v_mul_f32_e32 v41, v41, v203
	v_mul_f32_e32 v42, v42, v203
	v_mul_f32_e32 v43, v43, v203
	v_mul_f32_e32 v44, v44, v203
	v_mul_f32_e32 v45, v45, v203
	v_mul_f32_e32 v46, v46, v203
	v_mul_f32_e32 v47, v47, v203
	v_cvt_pk_bf16_f32 v210, v32, v33
	v_cvt_pk_bf16_f32 v211, v34, v35
	v_cvt_pk_bf16_f32 v212, v36, v37
	v_cvt_pk_bf16_f32 v213, v38, v39
	v_cvt_pk_bf16_f32 v214, v40, v41
	v_cvt_pk_bf16_f32 v215, v42, v43
	v_cvt_pk_bf16_f32 v216, v44, v45
	v_cvt_pk_bf16_f32 v217, v46, v47
	global_store_dwordx2 v167, v[210:211], s[98:99] offset:0
	global_store_dwordx2 v167, v[212:213], s[98:99] offset:32
	global_store_dwordx2 v167, v[214:215], s[98:99] offset:64
	global_store_dwordx2 v167, v[216:217], s[98:99] offset:96
	v_mov_b32_e32 v200, 0xf149f2ca
	v_mov_b32_e32 v201, 0
	v_mov_b32_e32 v32, 0
	v_mov_b32_e32 v33, 0
	v_mov_b32_e32 v34, 0
	v_mov_b32_e32 v35, 0
	v_mov_b32_e32 v36, 0
	v_mov_b32_e32 v37, 0
	v_mov_b32_e32 v38, 0
	v_mov_b32_e32 v39, 0
	v_mov_b32_e32 v40, 0
	v_mov_b32_e32 v41, 0
	v_mov_b32_e32 v42, 0
	v_mov_b32_e32 v43, 0
	v_mov_b32_e32 v44, 0
	v_mov_b32_e32 v45, 0
	v_mov_b32_e32 v46, 0
	v_mov_b32_e32 v47, 0
	v_mov_b32_e32 v64, v72
	v_mov_b32_e32 v65, v73
	v_mov_b32_e32 v66, v74
	v_mov_b32_e32 v67, v75
	v_mov_b32_e32 v68, v76
	v_mov_b32_e32 v69, v77
	v_mov_b32_e32 v70, v78
	v_mov_b32_e32 v71, v79
	s_add_u32 s3, s3, 1
	s_and_b32 s0, s3, 0xff
	s_cmp_lt_u32 s0, 16
	s_cbranch_scc1 .Lmy_att_tile
	s_waitcnt vmcnt(0)
	s_branch .LBB0_1501
